# k-loops: redundant s_setprio 0 / s_setprio 1 pair between the two 16-MFMA clusters of each phase removed (timing only)
# speedup vs baseline: 1.0019x; 1.0019x over previous
.LBB0_37:
	s_add_u32 s4, s54, 0xfffc0080
	s_addc_u32 s5, s55, -1
	s_add_i32 s61, 0, 0x10000
	s_cmp_eq_u32 s60, 12
	s_cselect_b32 s57, s29, s5
	s_cselect_b32 s56, s33, s4
	v_add_u32_e32 v138, s61, v150
	s_cselect_b32 s5, s47, s59
	s_cselect_b32 s4, s49, s58
	s_add_i32 s64, 0, 0x14000
	ds_read_b128 v[152:155], v138
	ds_read_b128 v[156:159], v138 offset:1024
	ds_read_b128 v[160:163], v138 offset:2048
	ds_read_b128 v[164:167], v138 offset:3072
	v_add_u32_e32 v138, s64, v150
	s_waitcnt vmcnt(8)
	ds_read_b128 v[168:171], v138
	ds_read_b128 v[172:175], v138 offset:1024
	ds_read_b128 v[184:187], v138 offset:2048
	ds_read_b128 v[188:191], v138 offset:3072
	v_lshl_add_u64 v[138:139], s[54:55], 0, v[142:143]
	s_add_i32 m0, s3, 0xc000
	ds_read_b128 v[192:195], v151
	ds_read_b128 v[196:199], v151 offset:1024
	ds_read_b128 v[200:203], v151 offset:2048
	ds_read_b128 v[204:207], v151 offset:3072
	ds_read_b128 v[208:211], v151 offset:4096
	ds_read_b128 v[212:215], v151 offset:5120
	ds_read_b128 v[216:219], v151 offset:6144
	ds_read_b128 v[220:223], v151 offset:7168
	global_load_lds_dwordx4 v[138:139], off
	v_lshl_add_u64 v[138:139], s[54:55], 0, v[144:145]
	s_add_i32 m0, s3, 0xe000
	s_nop 0
	global_load_lds_dwordx4 v[138:139], off
	s_waitcnt vmcnt(8)
	s_waitcnt lgkmcnt(0)
	s_barrier
	s_setprio 1
	s_waitcnt lgkmcnt(0)
	v_mfma_f32_16x16x32_bf16 v[126:129], v[152:155], v[192:195], v[126:129]
	v_mfma_f32_16x16x32_bf16 v[122:125], v[160:163], v[192:195], v[122:125]
	v_mfma_f32_16x16x32_bf16 v[110:113], v[152:155], v[200:203], v[110:113]
	v_mfma_f32_16x16x32_bf16 v[106:109], v[160:163], v[200:203], v[106:109]
	v_mfma_f32_16x16x32_bf16 v[94:97], v[152:155], v[208:211], v[94:97]
	v_mfma_f32_16x16x32_bf16 v[90:93], v[160:163], v[208:211], v[90:93]
	v_mfma_f32_16x16x32_bf16 v[78:81], v[152:155], v[216:219], v[78:81]
	v_mfma_f32_16x16x32_bf16 v[74:77], v[160:163], v[216:219], v[74:77]
	v_mfma_f32_16x16x32_bf16 v[126:129], v[156:159], v[196:199], v[126:129]
	v_mfma_f32_16x16x32_bf16 v[122:125], v[164:167], v[196:199], v[122:125]
	v_mfma_f32_16x16x32_bf16 v[110:113], v[156:159], v[204:207], v[110:113]
	v_mfma_f32_16x16x32_bf16 v[106:109], v[164:167], v[204:207], v[106:109]
	v_mfma_f32_16x16x32_bf16 v[94:97], v[156:159], v[212:215], v[94:97]
	v_mfma_f32_16x16x32_bf16 v[90:93], v[164:167], v[212:215], v[90:93]
	v_mfma_f32_16x16x32_bf16 v[78:81], v[156:159], v[220:223], v[78:81]
	v_mfma_f32_16x16x32_bf16 v[74:77], v[164:167], v[220:223], v[74:77]
	v_mfma_f32_16x16x32_bf16 v[118:121], v[168:171], v[192:195], v[118:121]
	v_mfma_f32_16x16x32_bf16 v[114:117], v[184:187], v[192:195], v[114:117]
	v_mfma_f32_16x16x32_bf16 v[102:105], v[168:171], v[200:203], v[102:105]
	v_mfma_f32_16x16x32_bf16 v[98:101], v[184:187], v[200:203], v[98:101]
	v_mfma_f32_16x16x32_bf16 v[86:89], v[168:171], v[208:211], v[86:89]
	v_mfma_f32_16x16x32_bf16 v[82:85], v[184:187], v[208:211], v[82:85]
	v_mfma_f32_16x16x32_bf16 v[70:73], v[168:171], v[216:219], v[70:73]
	v_mfma_f32_16x16x32_bf16 v[66:69], v[184:187], v[216:219], v[66:69]
	v_mfma_f32_16x16x32_bf16 v[118:121], v[172:175], v[196:199], v[118:121]
	v_mfma_f32_16x16x32_bf16 v[114:117], v[188:191], v[196:199], v[114:117]
	v_mfma_f32_16x16x32_bf16 v[102:105], v[172:175], v[204:207], v[102:105]
	v_mfma_f32_16x16x32_bf16 v[98:101], v[188:191], v[204:207], v[98:101]
	v_mfma_f32_16x16x32_bf16 v[86:89], v[172:175], v[212:215], v[86:89]
	v_mfma_f32_16x16x32_bf16 v[82:85], v[188:191], v[212:215], v[82:85]
	v_mfma_f32_16x16x32_bf16 v[70:73], v[172:175], v[220:223], v[70:73]
	v_mfma_f32_16x16x32_bf16 v[66:69], v[188:191], v[220:223], v[66:69]
	s_setprio 0
	s_barrier
	s_add_i32 s61, s61, s2
	v_lshl_add_u64 v[138:139], s[4:5], 0, v[134:135]
	s_mov_b32 m0, s61
	ds_read_b128 v[192:195], v151 offset:16384
	ds_read_b128 v[196:199], v151 offset:17408
	ds_read_b128 v[200:203], v151 offset:18432
	ds_read_b128 v[204:207], v151 offset:19456
	ds_read_b128 v[208:211], v151 offset:20480
	ds_read_b128 v[212:215], v151 offset:21504
	ds_read_b128 v[216:219], v151 offset:22528
	ds_read_b128 v[220:223], v151 offset:23552
	global_load_lds_dwordx4 v[138:139], off
	s_add_i32 m0, s61, 0x2000
	s_add_u32 s62, s4, 0x40000
	v_lshl_add_u64 v[148:149], s[4:5], 0, v[130:131]
	s_addc_u32 s63, s5, 0
	s_add_i32 s61, s64, s2
	global_load_lds_dwordx4 v[148:149], off
	v_lshl_add_u64 v[182:183], s[62:63], 0, v[134:135]
	s_mov_b32 m0, s61
	v_lshl_add_u64 v[224:225], s[56:57], 0, v[132:133]
	global_load_lds_dwordx4 v[182:183], off
	v_lshl_add_u64 v[182:183], s[62:63], 0, v[130:131]
	s_add_i32 m0, s61, 0x2000
	s_nop 0
	global_load_lds_dwordx4 v[182:183], off
	v_lshl_add_u64 v[182:183], s[56:57], 0, v[136:137]
	s_mov_b32 m0, s3
	s_nop 0
	global_load_lds_dwordx4 v[182:183], off
	s_mov_b32 m0, s10
	s_nop 0
	global_load_lds_dwordx4 v[224:225], off
	s_waitcnt vmcnt(8)
	s_waitcnt lgkmcnt(0)
	s_barrier
	s_setprio 1
	s_waitcnt lgkmcnt(0)
	v_mfma_f32_16x16x32_bf16 v[60:63], v[152:155], v[192:195], v[60:63]
	v_mfma_f32_16x16x32_bf16 v[56:59], v[160:163], v[192:195], v[56:59]
	v_mfma_f32_16x16x32_bf16 v[44:47], v[152:155], v[200:203], v[44:47]
	v_mfma_f32_16x16x32_bf16 v[40:43], v[160:163], v[200:203], v[40:43]
	v_mfma_f32_16x16x32_bf16 v[28:31], v[152:155], v[208:211], v[28:31]
	v_mfma_f32_16x16x32_bf16 v[24:27], v[160:163], v[208:211], v[24:27]
	v_mfma_f32_16x16x32_bf16 v[12:15], v[152:155], v[216:219], v[12:15]
	v_mfma_f32_16x16x32_bf16 v[8:11], v[160:163], v[216:219], v[8:11]
	v_mfma_f32_16x16x32_bf16 v[60:63], v[156:159], v[196:199], v[60:63]
	v_mfma_f32_16x16x32_bf16 v[56:59], v[164:167], v[196:199], v[56:59]
	v_mfma_f32_16x16x32_bf16 v[44:47], v[156:159], v[204:207], v[44:47]
	v_mfma_f32_16x16x32_bf16 v[40:43], v[164:167], v[204:207], v[40:43]
	v_mfma_f32_16x16x32_bf16 v[28:31], v[156:159], v[212:215], v[28:31]
	v_mfma_f32_16x16x32_bf16 v[24:27], v[164:167], v[212:215], v[24:27]
	v_mfma_f32_16x16x32_bf16 v[12:15], v[156:159], v[220:223], v[12:15]
	v_mfma_f32_16x16x32_bf16 v[8:11], v[164:167], v[220:223], v[8:11]
	v_mfma_f32_16x16x32_bf16 v[52:55], v[168:171], v[192:195], v[52:55]
	v_mfma_f32_16x16x32_bf16 v[48:51], v[184:187], v[192:195], v[48:51]
	v_mfma_f32_16x16x32_bf16 v[36:39], v[168:171], v[200:203], v[36:39]
	v_mfma_f32_16x16x32_bf16 v[32:35], v[184:187], v[200:203], v[32:35]
	v_mfma_f32_16x16x32_bf16 v[20:23], v[168:171], v[208:211], v[20:23]
	v_mfma_f32_16x16x32_bf16 v[16:19], v[184:187], v[208:211], v[16:19]
	v_mfma_f32_16x16x32_bf16 v[4:7], v[168:171], v[216:219], v[4:7]
	v_mfma_f32_16x16x32_bf16 v[0:3], v[184:187], v[216:219], v[0:3]
	v_mfma_f32_16x16x32_bf16 v[52:55], v[172:175], v[196:199], v[52:55]
	v_mfma_f32_16x16x32_bf16 v[48:51], v[188:191], v[196:199], v[48:51]
	v_mfma_f32_16x16x32_bf16 v[36:39], v[172:175], v[204:207], v[36:39]
	v_mfma_f32_16x16x32_bf16 v[32:35], v[188:191], v[204:207], v[32:35]
	v_mfma_f32_16x16x32_bf16 v[20:23], v[172:175], v[212:215], v[20:23]
	v_mfma_f32_16x16x32_bf16 v[16:19], v[188:191], v[212:215], v[16:19]
	v_mfma_f32_16x16x32_bf16 v[4:7], v[172:175], v[220:223], v[4:7]
	v_mfma_f32_16x16x32_bf16 v[0:3], v[188:191], v[220:223], v[0:3]
	s_setprio 0
	s_barrier
	s_add_i32 s61, 0, 0x18000
	v_add_u32_e32 v147, s61, v150
	s_add_i32 s62, 0, 0x1c000
	ds_read_b128 v[152:155], v147
	ds_read_b128 v[156:159], v147 offset:1024
	ds_read_b128 v[160:163], v147 offset:2048
	ds_read_b128 v[164:167], v147 offset:3072
	v_add_u32_e32 v147, s62, v150
	ds_read_b128 v[168:171], v147
	ds_read_b128 v[172:175], v147 offset:1024
	ds_read_b128 v[184:187], v147 offset:2048
	ds_read_b128 v[188:191], v147 offset:3072
	s_add_u32 s56, s56, 0x40000
	s_addc_u32 s57, s57, 0
	s_mov_b32 m0, s18
	v_lshl_add_u64 v[226:227], s[56:57], 0, v[136:137]
	ds_read_b128 v[192:195], v151 offset:32768
	ds_read_b128 v[196:199], v151 offset:33792
	ds_read_b128 v[200:203], v151 offset:34816
	ds_read_b128 v[204:207], v151 offset:35840
	ds_read_b128 v[208:211], v151 offset:36864
	ds_read_b128 v[212:215], v151 offset:37888
	ds_read_b128 v[216:219], v151 offset:38912
	ds_read_b128 v[220:223], v151 offset:39936
	global_load_lds_dwordx4 v[226:227], off
	v_lshl_add_u64 v[226:227], s[56:57], 0, v[132:133]
	s_mov_b32 m0, s19
	s_nop 0
	global_load_lds_dwordx4 v[226:227], off
	s_waitcnt vmcnt(8)
	s_waitcnt lgkmcnt(0)
	s_barrier
	s_setprio 1
	s_waitcnt lgkmcnt(0)
	v_mfma_f32_16x16x32_bf16 v[126:129], v[152:155], v[192:195], v[126:129]
	v_mfma_f32_16x16x32_bf16 v[122:125], v[160:163], v[192:195], v[122:125]
	v_mfma_f32_16x16x32_bf16 v[110:113], v[152:155], v[200:203], v[110:113]
	v_mfma_f32_16x16x32_bf16 v[106:109], v[160:163], v[200:203], v[106:109]
	v_mfma_f32_16x16x32_bf16 v[94:97], v[152:155], v[208:211], v[94:97]
	v_mfma_f32_16x16x32_bf16 v[90:93], v[160:163], v[208:211], v[90:93]
	v_mfma_f32_16x16x32_bf16 v[78:81], v[152:155], v[216:219], v[78:81]
	v_mfma_f32_16x16x32_bf16 v[74:77], v[160:163], v[216:219], v[74:77]
	v_mfma_f32_16x16x32_bf16 v[126:129], v[156:159], v[196:199], v[126:129]
	v_mfma_f32_16x16x32_bf16 v[122:125], v[164:167], v[196:199], v[122:125]
	v_mfma_f32_16x16x32_bf16 v[110:113], v[156:159], v[204:207], v[110:113]
	v_mfma_f32_16x16x32_bf16 v[106:109], v[164:167], v[204:207], v[106:109]
	v_mfma_f32_16x16x32_bf16 v[94:97], v[156:159], v[212:215], v[94:97]
	v_mfma_f32_16x16x32_bf16 v[90:93], v[164:167], v[212:215], v[90:93]
	v_mfma_f32_16x16x32_bf16 v[78:81], v[156:159], v[220:223], v[78:81]
	v_mfma_f32_16x16x32_bf16 v[74:77], v[164:167], v[220:223], v[74:77]
	v_mfma_f32_16x16x32_bf16 v[118:121], v[168:171], v[192:195], v[118:121]
	v_mfma_f32_16x16x32_bf16 v[114:117], v[184:187], v[192:195], v[114:117]
	v_mfma_f32_16x16x32_bf16 v[102:105], v[168:171], v[200:203], v[102:105]
	v_mfma_f32_16x16x32_bf16 v[98:101], v[184:187], v[200:203], v[98:101]
	v_mfma_f32_16x16x32_bf16 v[86:89], v[168:171], v[208:211], v[86:89]
	v_mfma_f32_16x16x32_bf16 v[82:85], v[184:187], v[208:211], v[82:85]
	v_mfma_f32_16x16x32_bf16 v[70:73], v[168:171], v[216:219], v[70:73]
	v_mfma_f32_16x16x32_bf16 v[66:69], v[184:187], v[216:219], v[66:69]
	v_mfma_f32_16x16x32_bf16 v[118:121], v[172:175], v[196:199], v[118:121]
	v_mfma_f32_16x16x32_bf16 v[114:117], v[188:191], v[196:199], v[114:117]
	v_mfma_f32_16x16x32_bf16 v[102:105], v[172:175], v[204:207], v[102:105]
	v_mfma_f32_16x16x32_bf16 v[98:101], v[188:191], v[204:207], v[98:101]
	v_mfma_f32_16x16x32_bf16 v[86:89], v[172:175], v[212:215], v[86:89]
	v_mfma_f32_16x16x32_bf16 v[82:85], v[188:191], v[212:215], v[82:85]
	v_mfma_f32_16x16x32_bf16 v[70:73], v[172:175], v[220:223], v[70:73]
	v_mfma_f32_16x16x32_bf16 v[66:69], v[188:191], v[220:223], v[66:69]
	s_setprio 0
	s_barrier
	s_add_i32 s56, s61, s2
	v_lshl_add_u64 v[138:139], v[138:139], 0, s[14:15]
	s_mov_b32 m0, s56
	ds_read_b128 v[192:195], v151 offset:49152
	ds_read_b128 v[196:199], v151 offset:50176
	ds_read_b128 v[200:203], v151 offset:51200
	ds_read_b128 v[204:207], v151 offset:52224
	ds_read_b128 v[208:211], v151 offset:53248
	ds_read_b128 v[212:215], v151 offset:54272
	ds_read_b128 v[216:219], v151 offset:55296
	ds_read_b128 v[220:223], v151 offset:56320
	global_load_lds_dwordx4 v[138:139], off
	s_add_i32 m0, s56, 0x2000
	s_add_u32 s4, s4, 0x40080
	v_lshl_add_u64 v[138:139], v[148:149], 0, s[14:15]
	s_addc_u32 s5, s5, 0
	s_add_i32 s56, s62, s2
	global_load_lds_dwordx4 v[138:139], off
	v_lshl_add_u64 v[138:139], s[4:5], 0, v[134:135]
	s_mov_b32 m0, s56
	s_nop 0
	global_load_lds_dwordx4 v[138:139], off
	v_lshl_add_u64 v[138:139], s[4:5], 0, v[130:131]
	s_add_i32 m0, s56, 0x2000
	s_nop 0
	global_load_lds_dwordx4 v[138:139], off
	v_lshl_add_u64 v[138:139], v[182:183], 0, s[14:15]
	s_mov_b32 m0, s20
	s_nop 0
	global_load_lds_dwordx4 v[138:139], off
	v_lshl_add_u64 v[138:139], v[224:225], 0, s[14:15]
	s_mov_b32 m0, s21
	s_nop 0
	global_load_lds_dwordx4 v[138:139], off
	s_waitcnt vmcnt(8)
	s_waitcnt lgkmcnt(0)
	s_barrier
	s_setprio 1
	s_waitcnt lgkmcnt(0)
	v_mfma_f32_16x16x32_bf16 v[60:63], v[152:155], v[192:195], v[60:63]
	v_mfma_f32_16x16x32_bf16 v[56:59], v[160:163], v[192:195], v[56:59]
	v_mfma_f32_16x16x32_bf16 v[44:47], v[152:155], v[200:203], v[44:47]
	v_mfma_f32_16x16x32_bf16 v[40:43], v[160:163], v[200:203], v[40:43]
	v_mfma_f32_16x16x32_bf16 v[28:31], v[152:155], v[208:211], v[28:31]
	v_mfma_f32_16x16x32_bf16 v[24:27], v[160:163], v[208:211], v[24:27]
	v_mfma_f32_16x16x32_bf16 v[12:15], v[152:155], v[216:219], v[12:15]
	v_mfma_f32_16x16x32_bf16 v[8:11], v[160:163], v[216:219], v[8:11]
	v_mfma_f32_16x16x32_bf16 v[60:63], v[156:159], v[196:199], v[60:63]
	v_mfma_f32_16x16x32_bf16 v[56:59], v[164:167], v[196:199], v[56:59]
	v_mfma_f32_16x16x32_bf16 v[44:47], v[156:159], v[204:207], v[44:47]
	v_mfma_f32_16x16x32_bf16 v[40:43], v[164:167], v[204:207], v[40:43]
	v_mfma_f32_16x16x32_bf16 v[28:31], v[156:159], v[212:215], v[28:31]
	v_mfma_f32_16x16x32_bf16 v[24:27], v[164:167], v[212:215], v[24:27]
	v_mfma_f32_16x16x32_bf16 v[12:15], v[156:159], v[220:223], v[12:15]
	v_mfma_f32_16x16x32_bf16 v[8:11], v[164:167], v[220:223], v[8:11]
	v_mfma_f32_16x16x32_bf16 v[52:55], v[168:171], v[192:195], v[52:55]
	v_mfma_f32_16x16x32_bf16 v[48:51], v[184:187], v[192:195], v[48:51]
	v_mfma_f32_16x16x32_bf16 v[36:39], v[168:171], v[200:203], v[36:39]
	v_mfma_f32_16x16x32_bf16 v[32:35], v[184:187], v[200:203], v[32:35]
	v_mfma_f32_16x16x32_bf16 v[20:23], v[168:171], v[208:211], v[20:23]
	v_mfma_f32_16x16x32_bf16 v[16:19], v[184:187], v[208:211], v[16:19]
	v_mfma_f32_16x16x32_bf16 v[4:7], v[168:171], v[216:219], v[4:7]
	v_mfma_f32_16x16x32_bf16 v[0:3], v[184:187], v[216:219], v[0:3]
	v_mfma_f32_16x16x32_bf16 v[52:55], v[172:175], v[196:199], v[52:55]
	v_mfma_f32_16x16x32_bf16 v[48:51], v[188:191], v[196:199], v[48:51]
	v_mfma_f32_16x16x32_bf16 v[36:39], v[172:175], v[204:207], v[36:39]
	v_mfma_f32_16x16x32_bf16 v[32:35], v[188:191], v[204:207], v[32:35]
	v_mfma_f32_16x16x32_bf16 v[20:23], v[172:175], v[212:215], v[20:23]
	v_mfma_f32_16x16x32_bf16 v[16:19], v[188:191], v[212:215], v[16:19]
	v_mfma_f32_16x16x32_bf16 v[4:7], v[172:175], v[220:223], v[4:7]
	v_mfma_f32_16x16x32_bf16 v[0:3], v[188:191], v[220:223], v[0:3]
	s_setprio 0
	s_barrier
	s_add_i32 s60, s60, 2
	s_add_u32 s54, s54, 0x100
	s_addc_u32 s55, s55, 0
	s_add_u32 s58, s58, 0x100
	s_addc_u32 s59, s59, 0
	s_cmp_gt_u32 s60, 13
	s_cbranch_scc0 .LBB0_37
	s_and_b64 vcc, exec, s[40:41]
	s_cbranch_vccz .LBB0_40
	s_barrier

.LBB0_66:
	s_add_u32 s4, s36, 0xfffc0080
	s_addc_u32 s5, s37, -1
	s_add_i32 s28, 0, 0x10000
	s_cmp_eq_u32 s25, 12
	s_cselect_b32 s55, s10, s5
	s_cselect_b32 s54, s18, s4
	v_add_u32_e32 v138, s28, v152
	s_cselect_b32 s5, s19, s24
	s_cselect_b32 s4, s20, s21
	s_add_i32 s33, 0, 0x14000
	ds_read_b128 v[154:157], v138
	ds_read_b128 v[158:161], v138 offset:1024
	ds_read_b128 v[162:165], v138 offset:2048
	ds_read_b128 v[166:169], v138 offset:3072
	v_add_u32_e32 v138, s33, v152
	s_waitcnt vmcnt(8)
	ds_read_b128 v[170:173], v138
	ds_read_b128 v[186:189], v138 offset:1024
	ds_read_b128 v[190:193], v138 offset:2048
	ds_read_b128 v[194:197], v138 offset:3072
	v_lshl_add_u64 v[138:139], s[36:37], 0, v[142:143]
	s_add_i32 m0, s57, 0xc000
	ds_read_b128 v[198:201], v153
	ds_read_b128 v[202:205], v153 offset:1024
	ds_read_b128 v[206:209], v153 offset:2048
	ds_read_b128 v[210:213], v153 offset:3072
	ds_read_b128 v[214:217], v153 offset:4096
	ds_read_b128 v[218:221], v153 offset:5120
	ds_read_b128 v[222:225], v153 offset:6144
	ds_read_b128 v[226:229], v153 offset:7168
	global_load_lds_dwordx4 v[138:139], off
	v_lshl_add_u64 v[138:139], s[36:37], 0, v[144:145]
	s_add_i32 m0, s57, 0xe000
	s_nop 0
	global_load_lds_dwordx4 v[138:139], off
	s_waitcnt vmcnt(8)
	s_waitcnt lgkmcnt(0)
	s_barrier
	s_setprio 1
	s_waitcnt lgkmcnt(0)
	v_mfma_f32_16x16x32_bf16 v[126:129], v[154:157], v[198:201], v[126:129]
	v_mfma_f32_16x16x32_bf16 v[122:125], v[162:165], v[198:201], v[122:125]
	v_mfma_f32_16x16x32_bf16 v[110:113], v[154:157], v[206:209], v[110:113]
	v_mfma_f32_16x16x32_bf16 v[106:109], v[162:165], v[206:209], v[106:109]
	v_mfma_f32_16x16x32_bf16 v[94:97], v[154:157], v[214:217], v[94:97]
	v_mfma_f32_16x16x32_bf16 v[90:93], v[162:165], v[214:217], v[90:93]
	v_mfma_f32_16x16x32_bf16 v[78:81], v[154:157], v[222:225], v[78:81]
	v_mfma_f32_16x16x32_bf16 v[74:77], v[162:165], v[222:225], v[74:77]
	v_mfma_f32_16x16x32_bf16 v[126:129], v[158:161], v[202:205], v[126:129]
	v_mfma_f32_16x16x32_bf16 v[122:125], v[166:169], v[202:205], v[122:125]
	v_mfma_f32_16x16x32_bf16 v[110:113], v[158:161], v[210:213], v[110:113]
	v_mfma_f32_16x16x32_bf16 v[106:109], v[166:169], v[210:213], v[106:109]
	v_mfma_f32_16x16x32_bf16 v[94:97], v[158:161], v[218:221], v[94:97]
	v_mfma_f32_16x16x32_bf16 v[90:93], v[166:169], v[218:221], v[90:93]
	v_mfma_f32_16x16x32_bf16 v[78:81], v[158:161], v[226:229], v[78:81]
	v_mfma_f32_16x16x32_bf16 v[74:77], v[166:169], v[226:229], v[74:77]
	v_mfma_f32_16x16x32_bf16 v[118:121], v[170:173], v[198:201], v[118:121]
	v_mfma_f32_16x16x32_bf16 v[114:117], v[190:193], v[198:201], v[114:117]
	v_mfma_f32_16x16x32_bf16 v[102:105], v[170:173], v[206:209], v[102:105]
	v_mfma_f32_16x16x32_bf16 v[98:101], v[190:193], v[206:209], v[98:101]
	v_mfma_f32_16x16x32_bf16 v[86:89], v[170:173], v[214:217], v[86:89]
	v_mfma_f32_16x16x32_bf16 v[82:85], v[190:193], v[214:217], v[82:85]
	v_mfma_f32_16x16x32_bf16 v[70:73], v[170:173], v[222:225], v[70:73]
	v_mfma_f32_16x16x32_bf16 v[66:69], v[190:193], v[222:225], v[66:69]
	v_mfma_f32_16x16x32_bf16 v[118:121], v[186:189], v[202:205], v[118:121]
	v_mfma_f32_16x16x32_bf16 v[114:117], v[194:197], v[202:205], v[114:117]
	v_mfma_f32_16x16x32_bf16 v[102:105], v[186:189], v[210:213], v[102:105]
	v_mfma_f32_16x16x32_bf16 v[98:101], v[194:197], v[210:213], v[98:101]
	v_mfma_f32_16x16x32_bf16 v[86:89], v[186:189], v[218:221], v[86:89]
	v_mfma_f32_16x16x32_bf16 v[82:85], v[194:197], v[218:221], v[82:85]
	v_mfma_f32_16x16x32_bf16 v[70:73], v[186:189], v[226:229], v[70:73]
	v_mfma_f32_16x16x32_bf16 v[66:69], v[194:197], v[226:229], v[66:69]
	s_setprio 0
	s_barrier
	s_add_i32 s28, s28, s56
	v_lshl_add_u64 v[138:139], s[4:5], 0, v[134:135]
	s_mov_b32 m0, s28
	ds_read_b128 v[198:201], v153 offset:16384
	ds_read_b128 v[202:205], v153 offset:17408
	ds_read_b128 v[206:209], v153 offset:18432
	ds_read_b128 v[210:213], v153 offset:19456
	ds_read_b128 v[214:217], v153 offset:20480
	ds_read_b128 v[218:221], v153 offset:21504
	ds_read_b128 v[222:225], v153 offset:22528
	ds_read_b128 v[226:229], v153 offset:23552
	global_load_lds_dwordx4 v[138:139], off
	s_add_i32 m0, s28, 0x2000
	s_add_u32 s28, s4, 0x40000
	v_lshl_add_u64 v[148:149], s[4:5], 0, v[130:131]
	s_addc_u32 s29, s5, 0
	s_add_i32 s33, s33, s56
	global_load_lds_dwordx4 v[148:149], off
	v_lshl_add_u64 v[174:175], s[28:29], 0, v[134:135]
	s_mov_b32 m0, s33
	v_lshl_add_u64 v[182:183], s[54:55], 0, v[132:133]
	global_load_lds_dwordx4 v[174:175], off
	v_lshl_add_u64 v[174:175], s[28:29], 0, v[130:131]
	s_add_i32 m0, s33, 0x2000
	s_nop 0
	global_load_lds_dwordx4 v[174:175], off
	v_lshl_add_u64 v[174:175], s[54:55], 0, v[136:137]
	s_mov_b32 m0, s57
	s_nop 0
	global_load_lds_dwordx4 v[174:175], off
	s_mov_b32 m0, s58
	s_nop 0
	global_load_lds_dwordx4 v[182:183], off
	s_waitcnt vmcnt(8)
	s_waitcnt lgkmcnt(0)
	s_barrier
	s_setprio 1
	s_waitcnt lgkmcnt(0)
	v_mfma_f32_16x16x32_bf16 v[60:63], v[154:157], v[198:201], v[60:63]
	v_mfma_f32_16x16x32_bf16 v[56:59], v[162:165], v[198:201], v[56:59]
	v_mfma_f32_16x16x32_bf16 v[44:47], v[154:157], v[206:209], v[44:47]
	v_mfma_f32_16x16x32_bf16 v[40:43], v[162:165], v[206:209], v[40:43]
	v_mfma_f32_16x16x32_bf16 v[28:31], v[154:157], v[214:217], v[28:31]
	v_mfma_f32_16x16x32_bf16 v[24:27], v[162:165], v[214:217], v[24:27]
	v_mfma_f32_16x16x32_bf16 v[12:15], v[154:157], v[222:225], v[12:15]
	v_mfma_f32_16x16x32_bf16 v[8:11], v[162:165], v[222:225], v[8:11]
	v_mfma_f32_16x16x32_bf16 v[60:63], v[158:161], v[202:205], v[60:63]
	v_mfma_f32_16x16x32_bf16 v[56:59], v[166:169], v[202:205], v[56:59]
	v_mfma_f32_16x16x32_bf16 v[44:47], v[158:161], v[210:213], v[44:47]
	v_mfma_f32_16x16x32_bf16 v[40:43], v[166:169], v[210:213], v[40:43]
	v_mfma_f32_16x16x32_bf16 v[28:31], v[158:161], v[218:221], v[28:31]
	v_mfma_f32_16x16x32_bf16 v[24:27], v[166:169], v[218:221], v[24:27]
	v_mfma_f32_16x16x32_bf16 v[12:15], v[158:161], v[226:229], v[12:15]
	v_mfma_f32_16x16x32_bf16 v[8:11], v[166:169], v[226:229], v[8:11]
	v_mfma_f32_16x16x32_bf16 v[52:55], v[170:173], v[198:201], v[52:55]
	v_mfma_f32_16x16x32_bf16 v[48:51], v[190:193], v[198:201], v[48:51]
	v_mfma_f32_16x16x32_bf16 v[36:39], v[170:173], v[206:209], v[36:39]
	v_mfma_f32_16x16x32_bf16 v[32:35], v[190:193], v[206:209], v[32:35]
	v_mfma_f32_16x16x32_bf16 v[20:23], v[170:173], v[214:217], v[20:23]
	v_mfma_f32_16x16x32_bf16 v[16:19], v[190:193], v[214:217], v[16:19]
	v_mfma_f32_16x16x32_bf16 v[4:7], v[170:173], v[222:225], v[4:7]
	v_mfma_f32_16x16x32_bf16 v[0:3], v[190:193], v[222:225], v[0:3]
	v_mfma_f32_16x16x32_bf16 v[52:55], v[186:189], v[202:205], v[52:55]
	v_mfma_f32_16x16x32_bf16 v[48:51], v[194:197], v[202:205], v[48:51]
	v_mfma_f32_16x16x32_bf16 v[36:39], v[186:189], v[210:213], v[36:39]
	v_mfma_f32_16x16x32_bf16 v[32:35], v[194:197], v[210:213], v[32:35]
	v_mfma_f32_16x16x32_bf16 v[20:23], v[186:189], v[218:221], v[20:23]
	v_mfma_f32_16x16x32_bf16 v[16:19], v[194:197], v[218:221], v[16:19]
	v_mfma_f32_16x16x32_bf16 v[4:7], v[186:189], v[226:229], v[4:7]
	v_mfma_f32_16x16x32_bf16 v[0:3], v[194:197], v[226:229], v[0:3]
	s_setprio 0
	s_barrier
	s_add_i32 s33, 0, 0x18000
	v_add_u32_e32 v147, s33, v152
	s_add_i32 s47, 0, 0x1c000
	ds_read_b128 v[154:157], v147
	ds_read_b128 v[158:161], v147 offset:1024
	ds_read_b128 v[162:165], v147 offset:2048
	ds_read_b128 v[166:169], v147 offset:3072
	v_add_u32_e32 v147, s47, v152
	ds_read_b128 v[170:173], v147
	ds_read_b128 v[186:189], v147 offset:1024
	ds_read_b128 v[190:193], v147 offset:2048
	ds_read_b128 v[194:197], v147 offset:3072
	s_add_u32 s28, s54, 0x40000
	s_addc_u32 s29, s55, 0
	s_mov_b32 m0, s59
	v_lshl_add_u64 v[230:231], s[28:29], 0, v[136:137]
	ds_read_b128 v[198:201], v153 offset:32768
	ds_read_b128 v[202:205], v153 offset:33792
	ds_read_b128 v[206:209], v153 offset:34816
	ds_read_b128 v[210:213], v153 offset:35840
	ds_read_b128 v[214:217], v153 offset:36864
	ds_read_b128 v[218:221], v153 offset:37888
	ds_read_b128 v[222:225], v153 offset:38912
	ds_read_b128 v[226:229], v153 offset:39936
	global_load_lds_dwordx4 v[230:231], off
	v_lshl_add_u64 v[230:231], s[28:29], 0, v[132:133]
	s_mov_b32 m0, s60
	s_nop 0
	global_load_lds_dwordx4 v[230:231], off
	s_waitcnt vmcnt(8)
	s_waitcnt lgkmcnt(0)
	s_barrier
	s_setprio 1
	s_waitcnt lgkmcnt(0)
	v_mfma_f32_16x16x32_bf16 v[126:129], v[154:157], v[198:201], v[126:129]
	v_mfma_f32_16x16x32_bf16 v[122:125], v[162:165], v[198:201], v[122:125]
	v_mfma_f32_16x16x32_bf16 v[110:113], v[154:157], v[206:209], v[110:113]
	v_mfma_f32_16x16x32_bf16 v[106:109], v[162:165], v[206:209], v[106:109]
	v_mfma_f32_16x16x32_bf16 v[94:97], v[154:157], v[214:217], v[94:97]
	v_mfma_f32_16x16x32_bf16 v[90:93], v[162:165], v[214:217], v[90:93]
	v_mfma_f32_16x16x32_bf16 v[78:81], v[154:157], v[222:225], v[78:81]
	v_mfma_f32_16x16x32_bf16 v[74:77], v[162:165], v[222:225], v[74:77]
	v_mfma_f32_16x16x32_bf16 v[126:129], v[158:161], v[202:205], v[126:129]
	v_mfma_f32_16x16x32_bf16 v[122:125], v[166:169], v[202:205], v[122:125]
	v_mfma_f32_16x16x32_bf16 v[110:113], v[158:161], v[210:213], v[110:113]
	v_mfma_f32_16x16x32_bf16 v[106:109], v[166:169], v[210:213], v[106:109]
	v_mfma_f32_16x16x32_bf16 v[94:97], v[158:161], v[218:221], v[94:97]
	v_mfma_f32_16x16x32_bf16 v[90:93], v[166:169], v[218:221], v[90:93]
	v_mfma_f32_16x16x32_bf16 v[78:81], v[158:161], v[226:229], v[78:81]
	v_mfma_f32_16x16x32_bf16 v[74:77], v[166:169], v[226:229], v[74:77]
	v_mfma_f32_16x16x32_bf16 v[118:121], v[170:173], v[198:201], v[118:121]
	v_mfma_f32_16x16x32_bf16 v[114:117], v[190:193], v[198:201], v[114:117]
	v_mfma_f32_16x16x32_bf16 v[102:105], v[170:173], v[206:209], v[102:105]
	v_mfma_f32_16x16x32_bf16 v[98:101], v[190:193], v[206:209], v[98:101]
	v_mfma_f32_16x16x32_bf16 v[86:89], v[170:173], v[214:217], v[86:89]
	v_mfma_f32_16x16x32_bf16 v[82:85], v[190:193], v[214:217], v[82:85]
	v_mfma_f32_16x16x32_bf16 v[70:73], v[170:173], v[222:225], v[70:73]
	v_mfma_f32_16x16x32_bf16 v[66:69], v[190:193], v[222:225], v[66:69]
	v_mfma_f32_16x16x32_bf16 v[118:121], v[186:189], v[202:205], v[118:121]
	v_mfma_f32_16x16x32_bf16 v[114:117], v[194:197], v[202:205], v[114:117]
	v_mfma_f32_16x16x32_bf16 v[102:105], v[186:189], v[210:213], v[102:105]
	v_mfma_f32_16x16x32_bf16 v[98:101], v[194:197], v[210:213], v[98:101]
	v_mfma_f32_16x16x32_bf16 v[86:89], v[186:189], v[218:221], v[86:89]
	v_mfma_f32_16x16x32_bf16 v[82:85], v[194:197], v[218:221], v[82:85]
	v_mfma_f32_16x16x32_bf16 v[70:73], v[186:189], v[226:229], v[70:73]
	v_mfma_f32_16x16x32_bf16 v[66:69], v[194:197], v[226:229], v[66:69]
	s_setprio 0
	s_barrier
	s_add_i32 s28, s33, s56
	v_lshl_add_u64 v[138:139], v[138:139], 0, s[14:15]
	s_mov_b32 m0, s28
	ds_read_b128 v[198:201], v153 offset:49152
	ds_read_b128 v[202:205], v153 offset:50176
	ds_read_b128 v[206:209], v153 offset:51200
	ds_read_b128 v[210:213], v153 offset:52224
	ds_read_b128 v[214:217], v153 offset:53248
	ds_read_b128 v[218:221], v153 offset:54272
	ds_read_b128 v[222:225], v153 offset:55296
	ds_read_b128 v[226:229], v153 offset:56320
	global_load_lds_dwordx4 v[138:139], off
	s_add_i32 m0, s28, 0x2000
	s_add_u32 s4, s4, 0x40080
	v_lshl_add_u64 v[138:139], v[148:149], 0, s[14:15]
	s_addc_u32 s5, s5, 0
	s_add_i32 s28, s47, s56
	global_load_lds_dwordx4 v[138:139], off
	v_lshl_add_u64 v[138:139], s[4:5], 0, v[134:135]
	s_mov_b32 m0, s28
	s_nop 0
	global_load_lds_dwordx4 v[138:139], off
	v_lshl_add_u64 v[138:139], s[4:5], 0, v[130:131]
	s_add_i32 m0, s28, 0x2000
	s_nop 0
	global_load_lds_dwordx4 v[138:139], off
	v_lshl_add_u64 v[138:139], v[174:175], 0, s[14:15]
	s_mov_b32 m0, s61
	s_nop 0
	global_load_lds_dwordx4 v[138:139], off
	v_lshl_add_u64 v[138:139], v[182:183], 0, s[14:15]
	s_mov_b32 m0, s62
	s_nop 0
	global_load_lds_dwordx4 v[138:139], off
	s_waitcnt vmcnt(8)
	s_waitcnt lgkmcnt(0)
	s_barrier
	s_setprio 1
	s_waitcnt lgkmcnt(0)
	v_mfma_f32_16x16x32_bf16 v[60:63], v[154:157], v[198:201], v[60:63]
	v_mfma_f32_16x16x32_bf16 v[56:59], v[162:165], v[198:201], v[56:59]
	v_mfma_f32_16x16x32_bf16 v[44:47], v[154:157], v[206:209], v[44:47]
	v_mfma_f32_16x16x32_bf16 v[40:43], v[162:165], v[206:209], v[40:43]
	v_mfma_f32_16x16x32_bf16 v[28:31], v[154:157], v[214:217], v[28:31]
	v_mfma_f32_16x16x32_bf16 v[24:27], v[162:165], v[214:217], v[24:27]
	v_mfma_f32_16x16x32_bf16 v[12:15], v[154:157], v[222:225], v[12:15]
	v_mfma_f32_16x16x32_bf16 v[8:11], v[162:165], v[222:225], v[8:11]
	v_mfma_f32_16x16x32_bf16 v[60:63], v[158:161], v[202:205], v[60:63]
	v_mfma_f32_16x16x32_bf16 v[56:59], v[166:169], v[202:205], v[56:59]
	v_mfma_f32_16x16x32_bf16 v[44:47], v[158:161], v[210:213], v[44:47]
	v_mfma_f32_16x16x32_bf16 v[40:43], v[166:169], v[210:213], v[40:43]
	v_mfma_f32_16x16x32_bf16 v[28:31], v[158:161], v[218:221], v[28:31]
	v_mfma_f32_16x16x32_bf16 v[24:27], v[166:169], v[218:221], v[24:27]
	v_mfma_f32_16x16x32_bf16 v[12:15], v[158:161], v[226:229], v[12:15]
	v_mfma_f32_16x16x32_bf16 v[8:11], v[166:169], v[226:229], v[8:11]
	v_mfma_f32_16x16x32_bf16 v[52:55], v[170:173], v[198:201], v[52:55]
	v_mfma_f32_16x16x32_bf16 v[48:51], v[190:193], v[198:201], v[48:51]
	v_mfma_f32_16x16x32_bf16 v[36:39], v[170:173], v[206:209], v[36:39]
	v_mfma_f32_16x16x32_bf16 v[32:35], v[190:193], v[206:209], v[32:35]
	v_mfma_f32_16x16x32_bf16 v[20:23], v[170:173], v[214:217], v[20:23]
	v_mfma_f32_16x16x32_bf16 v[16:19], v[190:193], v[214:217], v[16:19]
	v_mfma_f32_16x16x32_bf16 v[4:7], v[170:173], v[222:225], v[4:7]
	v_mfma_f32_16x16x32_bf16 v[0:3], v[190:193], v[222:225], v[0:3]
	v_mfma_f32_16x16x32_bf16 v[52:55], v[186:189], v[202:205], v[52:55]
	v_mfma_f32_16x16x32_bf16 v[48:51], v[194:197], v[202:205], v[48:51]
	v_mfma_f32_16x16x32_bf16 v[36:39], v[186:189], v[210:213], v[36:39]
	v_mfma_f32_16x16x32_bf16 v[32:35], v[194:197], v[210:213], v[32:35]
	v_mfma_f32_16x16x32_bf16 v[20:23], v[186:189], v[218:221], v[20:23]
	v_mfma_f32_16x16x32_bf16 v[16:19], v[194:197], v[218:221], v[16:19]
	v_mfma_f32_16x16x32_bf16 v[4:7], v[186:189], v[226:229], v[4:7]
	v_mfma_f32_16x16x32_bf16 v[0:3], v[194:197], v[226:229], v[0:3]
	s_setprio 0
	s_barrier
	s_add_i32 s25, s25, 2
	s_add_u32 s36, s36, 0x100
	s_addc_u32 s37, s37, 0
	s_add_u32 s21, s21, 0x100
	s_addc_u32 s24, s24, 0
	s_cmp_gt_u32 s25, 13
	s_cbranch_scc0 .LBB0_66
	s_and_b64 vcc, exec, s[40:41]
	s_cbranch_vccz .LBB0_69
	s_barrier

.LBB0_107:
	s_add_u32 s4, s56, 0xfffc0080
	s_addc_u32 s5, s57, -1
	s_add_i32 s64, 0, 0x10000
	s_cmp_eq_u32 s63, 12
	s_cselect_b32 s59, s33, s5
	s_cselect_b32 s58, s51, s4
	v_add_u32_e32 v138, s64, v173
	s_cselect_b32 s5, s49, s62
	s_cselect_b32 s4, s60, s61
	s_add_i32 s70, 0, 0x14000
	ds_read_b128 v[148:151], v138
	ds_read_b128 v[184:187], v138 offset:1024
	ds_read_b128 v[188:191], v138 offset:2048
	ds_read_b128 v[192:195], v138 offset:3072
	v_add_u32_e32 v138, s70, v173
	ds_read_b128 v[196:199], v138
	ds_read_b128 v[200:203], v138 offset:1024
	ds_read_b128 v[204:207], v138 offset:2048
	ds_read_b128 v[208:211], v138 offset:3072
	v_lshl_add_u64 v[182:183], s[56:57], 0, v[144:145]
	s_add_i32 m0, s3, 0xc000
	ds_read_b128 v[212:215], v174
	ds_read_b128 v[216:219], v174 offset:1024
	ds_read_b128 v[220:223], v174 offset:2048
	ds_read_b128 v[224:227], v174 offset:3072
	ds_read_b128 v[228:231], v174 offset:4096
	ds_read_b128 v[232:235], v174 offset:5120
	ds_read_b128 v[236:239], v174 offset:6144
	ds_read_b128 v[240:243], v174 offset:7168
	global_load_lds_dwordx4 v[182:183], off
	v_lshl_add_u64 v[182:183], s[56:57], 0, v[146:147]
	s_add_i32 m0, s3, 0xe000
	s_nop 0
	global_load_lds_dwordx4 v[182:183], off
	s_waitcnt vmcnt(8)
	s_waitcnt lgkmcnt(0)
	s_barrier
	s_setprio 1
	s_waitcnt lgkmcnt(0)
	v_mfma_f32_16x16x32_bf16 v[126:129], v[148:151], v[212:215], v[126:129]
	v_mfma_f32_16x16x32_bf16 v[122:125], v[188:191], v[212:215], v[122:125]
	v_mfma_f32_16x16x32_bf16 v[110:113], v[148:151], v[220:223], v[110:113]
	v_mfma_f32_16x16x32_bf16 v[106:109], v[188:191], v[220:223], v[106:109]
	v_mfma_f32_16x16x32_bf16 v[94:97], v[148:151], v[228:231], v[94:97]
	v_mfma_f32_16x16x32_bf16 v[90:93], v[188:191], v[228:231], v[90:93]
	v_mfma_f32_16x16x32_bf16 v[78:81], v[148:151], v[236:239], v[78:81]
	v_mfma_f32_16x16x32_bf16 v[74:77], v[188:191], v[236:239], v[74:77]
	v_mfma_f32_16x16x32_bf16 v[126:129], v[184:187], v[216:219], v[126:129]
	v_mfma_f32_16x16x32_bf16 v[122:125], v[192:195], v[216:219], v[122:125]
	v_mfma_f32_16x16x32_bf16 v[110:113], v[184:187], v[224:227], v[110:113]
	v_mfma_f32_16x16x32_bf16 v[106:109], v[192:195], v[224:227], v[106:109]
	v_mfma_f32_16x16x32_bf16 v[94:97], v[184:187], v[232:235], v[94:97]
	v_mfma_f32_16x16x32_bf16 v[90:93], v[192:195], v[232:235], v[90:93]
	v_mfma_f32_16x16x32_bf16 v[78:81], v[184:187], v[240:243], v[78:81]
	v_mfma_f32_16x16x32_bf16 v[74:77], v[192:195], v[240:243], v[74:77]
	v_mfma_f32_16x16x32_bf16 v[118:121], v[196:199], v[212:215], v[118:121]
	v_mfma_f32_16x16x32_bf16 v[114:117], v[204:207], v[212:215], v[114:117]
	v_mfma_f32_16x16x32_bf16 v[102:105], v[196:199], v[220:223], v[102:105]
	v_mfma_f32_16x16x32_bf16 v[98:101], v[204:207], v[220:223], v[98:101]
	v_mfma_f32_16x16x32_bf16 v[86:89], v[196:199], v[228:231], v[86:89]
	v_mfma_f32_16x16x32_bf16 v[82:85], v[204:207], v[228:231], v[82:85]
	v_mfma_f32_16x16x32_bf16 v[70:73], v[196:199], v[236:239], v[70:73]
	v_mfma_f32_16x16x32_bf16 v[66:69], v[204:207], v[236:239], v[66:69]
	v_mfma_f32_16x16x32_bf16 v[118:121], v[200:203], v[216:219], v[118:121]
	v_mfma_f32_16x16x32_bf16 v[114:117], v[208:211], v[216:219], v[114:117]
	v_mfma_f32_16x16x32_bf16 v[102:105], v[200:203], v[224:227], v[102:105]
	v_mfma_f32_16x16x32_bf16 v[98:101], v[208:211], v[224:227], v[98:101]
	v_mfma_f32_16x16x32_bf16 v[86:89], v[200:203], v[232:235], v[86:89]
	v_mfma_f32_16x16x32_bf16 v[82:85], v[208:211], v[232:235], v[82:85]
	v_mfma_f32_16x16x32_bf16 v[70:73], v[200:203], v[240:243], v[70:73]
	v_mfma_f32_16x16x32_bf16 v[66:69], v[208:211], v[240:243], v[66:69]
	s_setprio 0
	s_barrier
	s_add_i32 s64, s64, s2
	v_lshl_add_u64 v[182:183], s[4:5], 0, v[134:135]
	s_mov_b32 m0, s64
	ds_read_b128 v[212:215], v174 offset:16384
	ds_read_b128 v[216:219], v174 offset:17408
	ds_read_b128 v[220:223], v174 offset:18432
	ds_read_b128 v[224:227], v174 offset:19456
	ds_read_b128 v[228:231], v174 offset:20480
	ds_read_b128 v[232:235], v174 offset:21504
	ds_read_b128 v[236:239], v174 offset:22528
	ds_read_b128 v[240:243], v174 offset:23552
	global_load_lds_dwordx4 v[182:183], off
	s_add_i32 m0, s64, 0x2000
	s_add_u32 s64, s4, 0x40000
	v_lshl_add_u64 v[244:245], s[4:5], 0, v[130:131]
	s_addc_u32 s65, s5, 0
	s_add_i32 s70, s70, s2
	global_load_lds_dwordx4 v[244:245], off
	v_lshl_add_u64 v[246:247], s[64:65], 0, v[134:135]
	s_mov_b32 m0, s70
	v_lshl_add_u64 v[248:249], s[58:59], 0, v[132:133]
	global_load_lds_dwordx4 v[246:247], off
	v_lshl_add_u64 v[246:247], s[64:65], 0, v[130:131]
	s_add_i32 m0, s70, 0x2000
	s_nop 0
	global_load_lds_dwordx4 v[246:247], off
	v_lshl_add_u64 v[246:247], s[58:59], 0, v[136:137]
	s_mov_b32 m0, s3
	s_nop 0
	global_load_lds_dwordx4 v[246:247], off
	s_mov_b32 m0, s10
	s_nop 0
	global_load_lds_dwordx4 v[248:249], off
	s_waitcnt vmcnt(8)
	s_waitcnt lgkmcnt(0)
	s_barrier
	s_setprio 1
	s_waitcnt lgkmcnt(0)
	v_mfma_f32_16x16x32_bf16 v[60:63], v[148:151], v[212:215], v[60:63]
	v_mfma_f32_16x16x32_bf16 v[56:59], v[188:191], v[212:215], v[56:59]
	v_mfma_f32_16x16x32_bf16 v[44:47], v[148:151], v[220:223], v[44:47]
	v_mfma_f32_16x16x32_bf16 v[40:43], v[188:191], v[220:223], v[40:43]
	v_mfma_f32_16x16x32_bf16 v[28:31], v[148:151], v[228:231], v[28:31]
	v_mfma_f32_16x16x32_bf16 v[24:27], v[188:191], v[228:231], v[24:27]
	v_mfma_f32_16x16x32_bf16 v[12:15], v[148:151], v[236:239], v[12:15]
	v_mfma_f32_16x16x32_bf16 v[8:11], v[188:191], v[236:239], v[8:11]
	v_mfma_f32_16x16x32_bf16 v[60:63], v[184:187], v[216:219], v[60:63]
	v_mfma_f32_16x16x32_bf16 v[56:59], v[192:195], v[216:219], v[56:59]
	v_mfma_f32_16x16x32_bf16 v[44:47], v[184:187], v[224:227], v[44:47]
	v_mfma_f32_16x16x32_bf16 v[40:43], v[192:195], v[224:227], v[40:43]
	v_mfma_f32_16x16x32_bf16 v[28:31], v[184:187], v[232:235], v[28:31]
	v_mfma_f32_16x16x32_bf16 v[24:27], v[192:195], v[232:235], v[24:27]
	v_mfma_f32_16x16x32_bf16 v[12:15], v[184:187], v[240:243], v[12:15]
	v_mfma_f32_16x16x32_bf16 v[8:11], v[192:195], v[240:243], v[8:11]
	v_mfma_f32_16x16x32_bf16 v[52:55], v[196:199], v[212:215], v[52:55]
	v_mfma_f32_16x16x32_bf16 v[48:51], v[204:207], v[212:215], v[48:51]
	v_mfma_f32_16x16x32_bf16 v[36:39], v[196:199], v[220:223], v[36:39]
	v_mfma_f32_16x16x32_bf16 v[32:35], v[204:207], v[220:223], v[32:35]
	v_mfma_f32_16x16x32_bf16 v[20:23], v[196:199], v[228:231], v[20:23]
	v_mfma_f32_16x16x32_bf16 v[16:19], v[204:207], v[228:231], v[16:19]
	v_mfma_f32_16x16x32_bf16 v[4:7], v[196:199], v[236:239], v[4:7]
	v_mfma_f32_16x16x32_bf16 v[0:3], v[204:207], v[236:239], v[0:3]
	v_mfma_f32_16x16x32_bf16 v[52:55], v[200:203], v[216:219], v[52:55]
	v_mfma_f32_16x16x32_bf16 v[48:51], v[208:211], v[216:219], v[48:51]
	v_mfma_f32_16x16x32_bf16 v[36:39], v[200:203], v[224:227], v[36:39]
	v_mfma_f32_16x16x32_bf16 v[32:35], v[208:211], v[224:227], v[32:35]
	v_mfma_f32_16x16x32_bf16 v[20:23], v[200:203], v[232:235], v[20:23]
	v_mfma_f32_16x16x32_bf16 v[16:19], v[208:211], v[232:235], v[16:19]
	v_mfma_f32_16x16x32_bf16 v[4:7], v[200:203], v[240:243], v[4:7]
	v_mfma_f32_16x16x32_bf16 v[0:3], v[208:211], v[240:243], v[0:3]
	s_setprio 0
	s_barrier
	s_add_i32 s64, 0, 0x18000
	v_add_u32_e32 v138, s64, v173
	s_add_i32 s65, 0, 0x1c000
	ds_read_b128 v[148:151], v138
	ds_read_b128 v[184:187], v138 offset:1024
	ds_read_b128 v[188:191], v138 offset:2048
	ds_read_b128 v[192:195], v138 offset:3072
	v_add_u32_e32 v138, s65, v173
	ds_read_b128 v[196:199], v138
	ds_read_b128 v[200:203], v138 offset:1024
	ds_read_b128 v[204:207], v138 offset:2048
	ds_read_b128 v[208:211], v138 offset:3072
	s_add_u32 s58, s58, 0x40000
	s_addc_u32 s59, s59, 0
	s_mov_b32 m0, s18
	v_lshl_add_u64 v[138:139], s[58:59], 0, v[136:137]
	ds_read_b128 v[212:215], v174 offset:32768
	ds_read_b128 v[216:219], v174 offset:33792
	ds_read_b128 v[220:223], v174 offset:34816
	ds_read_b128 v[224:227], v174 offset:35840
	ds_read_b128 v[228:231], v174 offset:36864
	ds_read_b128 v[232:235], v174 offset:37888
	ds_read_b128 v[236:239], v174 offset:38912
	ds_read_b128 v[240:243], v174 offset:39936
	global_load_lds_dwordx4 v[138:139], off
	v_lshl_add_u64 v[138:139], s[58:59], 0, v[132:133]
	s_mov_b32 m0, s19
	s_nop 0
	global_load_lds_dwordx4 v[138:139], off
	s_waitcnt vmcnt(8)
	s_waitcnt lgkmcnt(0)
	s_barrier
	s_setprio 1
	s_waitcnt lgkmcnt(0)
	v_mfma_f32_16x16x32_bf16 v[126:129], v[148:151], v[212:215], v[126:129]
	v_mfma_f32_16x16x32_bf16 v[122:125], v[188:191], v[212:215], v[122:125]
	v_mfma_f32_16x16x32_bf16 v[110:113], v[148:151], v[220:223], v[110:113]
	v_mfma_f32_16x16x32_bf16 v[106:109], v[188:191], v[220:223], v[106:109]
	v_mfma_f32_16x16x32_bf16 v[94:97], v[148:151], v[228:231], v[94:97]
	v_mfma_f32_16x16x32_bf16 v[90:93], v[188:191], v[228:231], v[90:93]
	v_mfma_f32_16x16x32_bf16 v[78:81], v[148:151], v[236:239], v[78:81]
	v_mfma_f32_16x16x32_bf16 v[74:77], v[188:191], v[236:239], v[74:77]
	v_mfma_f32_16x16x32_bf16 v[126:129], v[184:187], v[216:219], v[126:129]
	v_mfma_f32_16x16x32_bf16 v[122:125], v[192:195], v[216:219], v[122:125]
	v_mfma_f32_16x16x32_bf16 v[110:113], v[184:187], v[224:227], v[110:113]
	v_mfma_f32_16x16x32_bf16 v[106:109], v[192:195], v[224:227], v[106:109]
	v_mfma_f32_16x16x32_bf16 v[94:97], v[184:187], v[232:235], v[94:97]
	v_mfma_f32_16x16x32_bf16 v[90:93], v[192:195], v[232:235], v[90:93]
	v_mfma_f32_16x16x32_bf16 v[78:81], v[184:187], v[240:243], v[78:81]
	v_mfma_f32_16x16x32_bf16 v[74:77], v[192:195], v[240:243], v[74:77]
	v_mfma_f32_16x16x32_bf16 v[118:121], v[196:199], v[212:215], v[118:121]
	v_mfma_f32_16x16x32_bf16 v[114:117], v[204:207], v[212:215], v[114:117]
	v_mfma_f32_16x16x32_bf16 v[102:105], v[196:199], v[220:223], v[102:105]
	v_mfma_f32_16x16x32_bf16 v[98:101], v[204:207], v[220:223], v[98:101]
	v_mfma_f32_16x16x32_bf16 v[86:89], v[196:199], v[228:231], v[86:89]
	v_mfma_f32_16x16x32_bf16 v[82:85], v[204:207], v[228:231], v[82:85]
	v_mfma_f32_16x16x32_bf16 v[70:73], v[196:199], v[236:239], v[70:73]
	v_mfma_f32_16x16x32_bf16 v[66:69], v[204:207], v[236:239], v[66:69]
	v_mfma_f32_16x16x32_bf16 v[118:121], v[200:203], v[216:219], v[118:121]
	v_mfma_f32_16x16x32_bf16 v[114:117], v[208:211], v[216:219], v[114:117]
	v_mfma_f32_16x16x32_bf16 v[102:105], v[200:203], v[224:227], v[102:105]
	v_mfma_f32_16x16x32_bf16 v[98:101], v[208:211], v[224:227], v[98:101]
	v_mfma_f32_16x16x32_bf16 v[86:89], v[200:203], v[232:235], v[86:89]
	v_mfma_f32_16x16x32_bf16 v[82:85], v[208:211], v[232:235], v[82:85]
	v_mfma_f32_16x16x32_bf16 v[70:73], v[200:203], v[240:243], v[70:73]
	v_mfma_f32_16x16x32_bf16 v[66:69], v[208:211], v[240:243], v[66:69]
	s_setprio 0
	s_barrier
	s_add_i32 s58, s64, s2
	v_lshl_add_u64 v[138:139], v[182:183], 0, s[14:15]
	s_mov_b32 m0, s58
	ds_read_b128 v[212:215], v174 offset:49152
	ds_read_b128 v[216:219], v174 offset:50176
	ds_read_b128 v[220:223], v174 offset:51200
	ds_read_b128 v[224:227], v174 offset:52224
	ds_read_b128 v[228:231], v174 offset:53248
	ds_read_b128 v[232:235], v174 offset:54272
	ds_read_b128 v[236:239], v174 offset:55296
	ds_read_b128 v[240:243], v174 offset:56320
	global_load_lds_dwordx4 v[138:139], off
	s_add_i32 m0, s58, 0x2000
	s_add_u32 s4, s4, 0x40080
	v_lshl_add_u64 v[138:139], v[244:245], 0, s[14:15]
	s_addc_u32 s5, s5, 0
	s_add_i32 s58, s65, s2
	global_load_lds_dwordx4 v[138:139], off
	v_lshl_add_u64 v[138:139], s[4:5], 0, v[134:135]
	s_mov_b32 m0, s58
	s_nop 0
	global_load_lds_dwordx4 v[138:139], off
	v_lshl_add_u64 v[138:139], s[4:5], 0, v[130:131]
	s_add_i32 m0, s58, 0x2000
	s_nop 0
	global_load_lds_dwordx4 v[138:139], off
	v_lshl_add_u64 v[138:139], v[246:247], 0, s[14:15]
	s_mov_b32 m0, s20
	s_nop 0
	global_load_lds_dwordx4 v[138:139], off
	v_lshl_add_u64 v[138:139], v[248:249], 0, s[14:15]
	s_mov_b32 m0, s21
	s_nop 0
	global_load_lds_dwordx4 v[138:139], off
	s_waitcnt vmcnt(8)
	s_waitcnt lgkmcnt(0)
	s_barrier
	s_setprio 1
	s_waitcnt lgkmcnt(0)
	v_mfma_f32_16x16x32_bf16 v[60:63], v[148:151], v[212:215], v[60:63]
	v_mfma_f32_16x16x32_bf16 v[56:59], v[188:191], v[212:215], v[56:59]
	v_mfma_f32_16x16x32_bf16 v[44:47], v[148:151], v[220:223], v[44:47]
	v_mfma_f32_16x16x32_bf16 v[40:43], v[188:191], v[220:223], v[40:43]
	v_mfma_f32_16x16x32_bf16 v[28:31], v[148:151], v[228:231], v[28:31]
	v_mfma_f32_16x16x32_bf16 v[24:27], v[188:191], v[228:231], v[24:27]
	v_mfma_f32_16x16x32_bf16 v[12:15], v[148:151], v[236:239], v[12:15]
	v_mfma_f32_16x16x32_bf16 v[8:11], v[188:191], v[236:239], v[8:11]
	v_mfma_f32_16x16x32_bf16 v[60:63], v[184:187], v[216:219], v[60:63]
	v_mfma_f32_16x16x32_bf16 v[56:59], v[192:195], v[216:219], v[56:59]
	v_mfma_f32_16x16x32_bf16 v[44:47], v[184:187], v[224:227], v[44:47]
	v_mfma_f32_16x16x32_bf16 v[40:43], v[192:195], v[224:227], v[40:43]
	v_mfma_f32_16x16x32_bf16 v[28:31], v[184:187], v[232:235], v[28:31]
	v_mfma_f32_16x16x32_bf16 v[24:27], v[192:195], v[232:235], v[24:27]
	v_mfma_f32_16x16x32_bf16 v[12:15], v[184:187], v[240:243], v[12:15]
	v_mfma_f32_16x16x32_bf16 v[8:11], v[192:195], v[240:243], v[8:11]
	v_mfma_f32_16x16x32_bf16 v[52:55], v[196:199], v[212:215], v[52:55]
	v_mfma_f32_16x16x32_bf16 v[48:51], v[204:207], v[212:215], v[48:51]
	v_mfma_f32_16x16x32_bf16 v[36:39], v[196:199], v[220:223], v[36:39]
	v_mfma_f32_16x16x32_bf16 v[32:35], v[204:207], v[220:223], v[32:35]
	v_mfma_f32_16x16x32_bf16 v[20:23], v[196:199], v[228:231], v[20:23]
	v_mfma_f32_16x16x32_bf16 v[16:19], v[204:207], v[228:231], v[16:19]
	v_mfma_f32_16x16x32_bf16 v[4:7], v[196:199], v[236:239], v[4:7]
	v_mfma_f32_16x16x32_bf16 v[0:3], v[204:207], v[236:239], v[0:3]
	v_mfma_f32_16x16x32_bf16 v[52:55], v[200:203], v[216:219], v[52:55]
	v_mfma_f32_16x16x32_bf16 v[48:51], v[208:211], v[216:219], v[48:51]
	v_mfma_f32_16x16x32_bf16 v[36:39], v[200:203], v[224:227], v[36:39]
	v_mfma_f32_16x16x32_bf16 v[32:35], v[208:211], v[224:227], v[32:35]
	v_mfma_f32_16x16x32_bf16 v[20:23], v[200:203], v[232:235], v[20:23]
	v_mfma_f32_16x16x32_bf16 v[16:19], v[208:211], v[232:235], v[16:19]
	v_mfma_f32_16x16x32_bf16 v[4:7], v[200:203], v[240:243], v[4:7]
	v_mfma_f32_16x16x32_bf16 v[0:3], v[208:211], v[240:243], v[0:3]
	s_setprio 0
	s_barrier
	s_add_i32 s63, s63, 2
	s_add_u32 s56, s56, 0x100
	s_addc_u32 s57, s57, 0
	s_add_u32 s61, s61, 0x100
	s_addc_u32 s62, s62, 0
	s_cmp_gt_u32 s63, 13
	s_cbranch_scc0 .LBB0_107
	s_and_b64 vcc, exec, s[46:47]
	s_cbranch_vccz .LBB0_110
	s_barrier

.LBB0_146:
	s_add_u32 s4, s54, 0xfff00080
	s_addc_u32 s5, s55, -1
	s_add_i32 s62, 0, 0x10000
	s_cmp_eq_u32 s61, 60
	s_cselect_b32 s57, s33, s5
	s_cselect_b32 s56, s49, s4
	v_add_u32_e32 v138, s62, v173
	s_cselect_b32 s5, s47, s60
	s_cselect_b32 s4, s58, s59
	s_add_i32 s64, 0, 0x14000
	ds_read_b128 v[148:151], v138
	ds_read_b128 v[184:187], v138 offset:1024
	ds_read_b128 v[188:191], v138 offset:2048
	ds_read_b128 v[192:195], v138 offset:3072
	v_add_u32_e32 v138, s64, v173
	ds_read_b128 v[196:199], v138
	ds_read_b128 v[200:203], v138 offset:1024
	ds_read_b128 v[204:207], v138 offset:2048
	ds_read_b128 v[208:211], v138 offset:3072
	v_lshl_add_u64 v[138:139], s[54:55], 0, v[144:145]
	s_add_i32 m0, s3, 0xc000
	ds_read_b128 v[212:215], v174
	ds_read_b128 v[216:219], v174 offset:1024
	ds_read_b128 v[220:223], v174 offset:2048
	ds_read_b128 v[224:227], v174 offset:3072
	ds_read_b128 v[228:231], v174 offset:4096
	ds_read_b128 v[232:235], v174 offset:5120
	ds_read_b128 v[236:239], v174 offset:6144
	ds_read_b128 v[240:243], v174 offset:7168
	global_load_lds_dwordx4 v[138:139], off
	v_lshl_add_u64 v[138:139], s[54:55], 0, v[146:147]
	s_add_i32 m0, s3, 0xe000
	s_nop 0
	global_load_lds_dwordx4 v[138:139], off
	s_waitcnt vmcnt(8)
	s_waitcnt lgkmcnt(0)
	s_barrier
	s_setprio 1
	s_waitcnt lgkmcnt(0)
	v_mfma_f32_16x16x32_bf16 v[126:129], v[148:151], v[212:215], v[126:129]
	v_mfma_f32_16x16x32_bf16 v[122:125], v[188:191], v[212:215], v[122:125]
	v_mfma_f32_16x16x32_bf16 v[110:113], v[148:151], v[220:223], v[110:113]
	v_mfma_f32_16x16x32_bf16 v[106:109], v[188:191], v[220:223], v[106:109]
	v_mfma_f32_16x16x32_bf16 v[94:97], v[148:151], v[228:231], v[94:97]
	v_mfma_f32_16x16x32_bf16 v[90:93], v[188:191], v[228:231], v[90:93]
	v_mfma_f32_16x16x32_bf16 v[78:81], v[148:151], v[236:239], v[78:81]
	v_mfma_f32_16x16x32_bf16 v[74:77], v[188:191], v[236:239], v[74:77]
	v_mfma_f32_16x16x32_bf16 v[126:129], v[184:187], v[216:219], v[126:129]
	v_mfma_f32_16x16x32_bf16 v[122:125], v[192:195], v[216:219], v[122:125]
	v_mfma_f32_16x16x32_bf16 v[110:113], v[184:187], v[224:227], v[110:113]
	v_mfma_f32_16x16x32_bf16 v[106:109], v[192:195], v[224:227], v[106:109]
	v_mfma_f32_16x16x32_bf16 v[94:97], v[184:187], v[232:235], v[94:97]
	v_mfma_f32_16x16x32_bf16 v[90:93], v[192:195], v[232:235], v[90:93]
	v_mfma_f32_16x16x32_bf16 v[78:81], v[184:187], v[240:243], v[78:81]
	v_mfma_f32_16x16x32_bf16 v[74:77], v[192:195], v[240:243], v[74:77]
	v_mfma_f32_16x16x32_bf16 v[118:121], v[196:199], v[212:215], v[118:121]
	v_mfma_f32_16x16x32_bf16 v[114:117], v[204:207], v[212:215], v[114:117]
	v_mfma_f32_16x16x32_bf16 v[102:105], v[196:199], v[220:223], v[102:105]
	v_mfma_f32_16x16x32_bf16 v[98:101], v[204:207], v[220:223], v[98:101]
	v_mfma_f32_16x16x32_bf16 v[86:89], v[196:199], v[228:231], v[86:89]
	v_mfma_f32_16x16x32_bf16 v[82:85], v[204:207], v[228:231], v[82:85]
	v_mfma_f32_16x16x32_bf16 v[70:73], v[196:199], v[236:239], v[70:73]
	v_mfma_f32_16x16x32_bf16 v[66:69], v[204:207], v[236:239], v[66:69]
	v_mfma_f32_16x16x32_bf16 v[118:121], v[200:203], v[216:219], v[118:121]
	v_mfma_f32_16x16x32_bf16 v[114:117], v[208:211], v[216:219], v[114:117]
	v_mfma_f32_16x16x32_bf16 v[102:105], v[200:203], v[224:227], v[102:105]
	v_mfma_f32_16x16x32_bf16 v[98:101], v[208:211], v[224:227], v[98:101]
	v_mfma_f32_16x16x32_bf16 v[86:89], v[200:203], v[232:235], v[86:89]
	v_mfma_f32_16x16x32_bf16 v[82:85], v[208:211], v[232:235], v[82:85]
	v_mfma_f32_16x16x32_bf16 v[70:73], v[200:203], v[240:243], v[70:73]
	v_mfma_f32_16x16x32_bf16 v[66:69], v[208:211], v[240:243], v[66:69]
	s_setprio 0
	s_barrier
	s_add_i32 s62, s62, s2
	v_lshl_add_u64 v[138:139], s[4:5], 0, v[134:135]
	s_mov_b32 m0, s62
	ds_read_b128 v[212:215], v174 offset:16384
	ds_read_b128 v[216:219], v174 offset:17408
	ds_read_b128 v[220:223], v174 offset:18432
	ds_read_b128 v[224:227], v174 offset:19456
	ds_read_b128 v[228:231], v174 offset:20480
	ds_read_b128 v[232:235], v174 offset:21504
	ds_read_b128 v[236:239], v174 offset:22528
	ds_read_b128 v[240:243], v174 offset:23552
	global_load_lds_dwordx4 v[138:139], off
	s_add_i32 m0, s62, 0x2000
	s_add_u32 s62, s4, 0x100000
	v_lshl_add_u64 v[182:183], s[4:5], 0, v[130:131]
	s_addc_u32 s63, s5, 0
	s_add_i32 s64, s64, s2
	global_load_lds_dwordx4 v[182:183], off
	v_lshl_add_u64 v[244:245], s[62:63], 0, v[134:135]
	s_mov_b32 m0, s64
	v_lshl_add_u64 v[246:247], s[56:57], 0, v[132:133]
	global_load_lds_dwordx4 v[244:245], off
	v_lshl_add_u64 v[244:245], s[62:63], 0, v[130:131]
	s_add_i32 m0, s64, 0x2000
	s_nop 0
	global_load_lds_dwordx4 v[244:245], off
	v_lshl_add_u64 v[244:245], s[56:57], 0, v[136:137]
	s_mov_b32 m0, s3
	s_nop 0
	global_load_lds_dwordx4 v[244:245], off
	s_mov_b32 m0, s10
	s_nop 0
	global_load_lds_dwordx4 v[246:247], off
	s_waitcnt vmcnt(8)
	s_waitcnt lgkmcnt(0)
	s_barrier
	s_setprio 1
	s_waitcnt lgkmcnt(0)
	v_mfma_f32_16x16x32_bf16 v[60:63], v[148:151], v[212:215], v[60:63]
	v_mfma_f32_16x16x32_bf16 v[56:59], v[188:191], v[212:215], v[56:59]
	v_mfma_f32_16x16x32_bf16 v[44:47], v[148:151], v[220:223], v[44:47]
	v_mfma_f32_16x16x32_bf16 v[40:43], v[188:191], v[220:223], v[40:43]
	v_mfma_f32_16x16x32_bf16 v[28:31], v[148:151], v[228:231], v[28:31]
	v_mfma_f32_16x16x32_bf16 v[24:27], v[188:191], v[228:231], v[24:27]
	v_mfma_f32_16x16x32_bf16 v[12:15], v[148:151], v[236:239], v[12:15]
	v_mfma_f32_16x16x32_bf16 v[8:11], v[188:191], v[236:239], v[8:11]
	v_mfma_f32_16x16x32_bf16 v[60:63], v[184:187], v[216:219], v[60:63]
	v_mfma_f32_16x16x32_bf16 v[56:59], v[192:195], v[216:219], v[56:59]
	v_mfma_f32_16x16x32_bf16 v[44:47], v[184:187], v[224:227], v[44:47]
	v_mfma_f32_16x16x32_bf16 v[40:43], v[192:195], v[224:227], v[40:43]
	v_mfma_f32_16x16x32_bf16 v[28:31], v[184:187], v[232:235], v[28:31]
	v_mfma_f32_16x16x32_bf16 v[24:27], v[192:195], v[232:235], v[24:27]
	v_mfma_f32_16x16x32_bf16 v[12:15], v[184:187], v[240:243], v[12:15]
	v_mfma_f32_16x16x32_bf16 v[8:11], v[192:195], v[240:243], v[8:11]
	v_mfma_f32_16x16x32_bf16 v[52:55], v[196:199], v[212:215], v[52:55]
	v_mfma_f32_16x16x32_bf16 v[48:51], v[204:207], v[212:215], v[48:51]
	v_mfma_f32_16x16x32_bf16 v[36:39], v[196:199], v[220:223], v[36:39]
	v_mfma_f32_16x16x32_bf16 v[32:35], v[204:207], v[220:223], v[32:35]
	v_mfma_f32_16x16x32_bf16 v[20:23], v[196:199], v[228:231], v[20:23]
	v_mfma_f32_16x16x32_bf16 v[16:19], v[204:207], v[228:231], v[16:19]
	v_mfma_f32_16x16x32_bf16 v[4:7], v[196:199], v[236:239], v[4:7]
	v_mfma_f32_16x16x32_bf16 v[0:3], v[204:207], v[236:239], v[0:3]
	v_mfma_f32_16x16x32_bf16 v[52:55], v[200:203], v[216:219], v[52:55]
	v_mfma_f32_16x16x32_bf16 v[48:51], v[208:211], v[216:219], v[48:51]
	v_mfma_f32_16x16x32_bf16 v[36:39], v[200:203], v[224:227], v[36:39]
	v_mfma_f32_16x16x32_bf16 v[32:35], v[208:211], v[224:227], v[32:35]
	v_mfma_f32_16x16x32_bf16 v[20:23], v[200:203], v[232:235], v[20:23]
	v_mfma_f32_16x16x32_bf16 v[16:19], v[208:211], v[232:235], v[16:19]
	v_mfma_f32_16x16x32_bf16 v[4:7], v[200:203], v[240:243], v[4:7]
	v_mfma_f32_16x16x32_bf16 v[0:3], v[208:211], v[240:243], v[0:3]
	s_setprio 0
	s_barrier
	s_add_i32 s62, 0, 0x18000
	v_add_u32_e32 v175, s62, v173
	s_add_i32 s63, 0, 0x1c000
	ds_read_b128 v[148:151], v175
	ds_read_b128 v[184:187], v175 offset:1024
	ds_read_b128 v[188:191], v175 offset:2048
	ds_read_b128 v[192:195], v175 offset:3072
	v_add_u32_e32 v175, s63, v173
	ds_read_b128 v[196:199], v175
	ds_read_b128 v[200:203], v175 offset:1024
	ds_read_b128 v[204:207], v175 offset:2048
	ds_read_b128 v[208:211], v175 offset:3072
	s_add_u32 s56, s56, 0x100000
	s_addc_u32 s57, s57, 0
	s_mov_b32 m0, s18
	v_lshl_add_u64 v[248:249], s[56:57], 0, v[136:137]
	ds_read_b128 v[212:215], v174 offset:32768
	ds_read_b128 v[216:219], v174 offset:33792
	ds_read_b128 v[220:223], v174 offset:34816
	ds_read_b128 v[224:227], v174 offset:35840
	ds_read_b128 v[228:231], v174 offset:36864
	ds_read_b128 v[232:235], v174 offset:37888
	ds_read_b128 v[236:239], v174 offset:38912
	ds_read_b128 v[240:243], v174 offset:39936
	global_load_lds_dwordx4 v[248:249], off
	v_lshl_add_u64 v[248:249], s[56:57], 0, v[132:133]
	s_mov_b32 m0, s19
	s_nop 0
	global_load_lds_dwordx4 v[248:249], off
	s_waitcnt vmcnt(8)
	s_waitcnt lgkmcnt(0)
	s_barrier
	s_setprio 1
	s_waitcnt lgkmcnt(0)
	v_mfma_f32_16x16x32_bf16 v[126:129], v[148:151], v[212:215], v[126:129]
	v_mfma_f32_16x16x32_bf16 v[122:125], v[188:191], v[212:215], v[122:125]
	v_mfma_f32_16x16x32_bf16 v[110:113], v[148:151], v[220:223], v[110:113]
	v_mfma_f32_16x16x32_bf16 v[106:109], v[188:191], v[220:223], v[106:109]
	v_mfma_f32_16x16x32_bf16 v[94:97], v[148:151], v[228:231], v[94:97]
	v_mfma_f32_16x16x32_bf16 v[90:93], v[188:191], v[228:231], v[90:93]
	v_mfma_f32_16x16x32_bf16 v[78:81], v[148:151], v[236:239], v[78:81]
	v_mfma_f32_16x16x32_bf16 v[74:77], v[188:191], v[236:239], v[74:77]
	v_mfma_f32_16x16x32_bf16 v[126:129], v[184:187], v[216:219], v[126:129]
	v_mfma_f32_16x16x32_bf16 v[122:125], v[192:195], v[216:219], v[122:125]
	v_mfma_f32_16x16x32_bf16 v[110:113], v[184:187], v[224:227], v[110:113]
	v_mfma_f32_16x16x32_bf16 v[106:109], v[192:195], v[224:227], v[106:109]
	v_mfma_f32_16x16x32_bf16 v[94:97], v[184:187], v[232:235], v[94:97]
	v_mfma_f32_16x16x32_bf16 v[90:93], v[192:195], v[232:235], v[90:93]
	v_mfma_f32_16x16x32_bf16 v[78:81], v[184:187], v[240:243], v[78:81]
	v_mfma_f32_16x16x32_bf16 v[74:77], v[192:195], v[240:243], v[74:77]
	v_mfma_f32_16x16x32_bf16 v[118:121], v[196:199], v[212:215], v[118:121]
	v_mfma_f32_16x16x32_bf16 v[114:117], v[204:207], v[212:215], v[114:117]
	v_mfma_f32_16x16x32_bf16 v[102:105], v[196:199], v[220:223], v[102:105]
	v_mfma_f32_16x16x32_bf16 v[98:101], v[204:207], v[220:223], v[98:101]
	v_mfma_f32_16x16x32_bf16 v[86:89], v[196:199], v[228:231], v[86:89]
	v_mfma_f32_16x16x32_bf16 v[82:85], v[204:207], v[228:231], v[82:85]
	v_mfma_f32_16x16x32_bf16 v[70:73], v[196:199], v[236:239], v[70:73]
	v_mfma_f32_16x16x32_bf16 v[66:69], v[204:207], v[236:239], v[66:69]
	v_mfma_f32_16x16x32_bf16 v[118:121], v[200:203], v[216:219], v[118:121]
	v_mfma_f32_16x16x32_bf16 v[114:117], v[208:211], v[216:219], v[114:117]
	v_mfma_f32_16x16x32_bf16 v[102:105], v[200:203], v[224:227], v[102:105]
	v_mfma_f32_16x16x32_bf16 v[98:101], v[208:211], v[224:227], v[98:101]
	v_mfma_f32_16x16x32_bf16 v[86:89], v[200:203], v[232:235], v[86:89]
	v_mfma_f32_16x16x32_bf16 v[82:85], v[208:211], v[232:235], v[82:85]
	v_mfma_f32_16x16x32_bf16 v[70:73], v[200:203], v[240:243], v[70:73]
	v_mfma_f32_16x16x32_bf16 v[66:69], v[208:211], v[240:243], v[66:69]
	s_setprio 0
	s_barrier
	s_add_i32 s56, s62, s2
	v_lshl_add_u64 v[138:139], v[138:139], 0, s[14:15]
	s_mov_b32 m0, s56
	ds_read_b128 v[212:215], v174 offset:49152
	ds_read_b128 v[216:219], v174 offset:50176
	ds_read_b128 v[220:223], v174 offset:51200
	ds_read_b128 v[224:227], v174 offset:52224
	ds_read_b128 v[228:231], v174 offset:53248
	ds_read_b128 v[232:235], v174 offset:54272
	ds_read_b128 v[236:239], v174 offset:55296
	ds_read_b128 v[240:243], v174 offset:56320
	global_load_lds_dwordx4 v[138:139], off
	s_add_i32 m0, s56, 0x2000
	s_add_u32 s4, s4, 0x100080
	v_lshl_add_u64 v[138:139], v[182:183], 0, s[14:15]
	s_addc_u32 s5, s5, 0
	s_add_i32 s56, s63, s2
	global_load_lds_dwordx4 v[138:139], off
	v_lshl_add_u64 v[138:139], s[4:5], 0, v[134:135]
	s_mov_b32 m0, s56
	s_nop 0
	global_load_lds_dwordx4 v[138:139], off
	v_lshl_add_u64 v[138:139], s[4:5], 0, v[130:131]
	s_add_i32 m0, s56, 0x2000
	s_nop 0
	global_load_lds_dwordx4 v[138:139], off
	v_lshl_add_u64 v[138:139], v[244:245], 0, s[14:15]
	s_mov_b32 m0, s20
	s_nop 0
	global_load_lds_dwordx4 v[138:139], off
	v_lshl_add_u64 v[138:139], v[246:247], 0, s[14:15]
	s_mov_b32 m0, s21
	s_nop 0
	global_load_lds_dwordx4 v[138:139], off
	s_waitcnt vmcnt(8)
	s_waitcnt lgkmcnt(0)
	s_barrier
	s_setprio 1
	s_waitcnt lgkmcnt(0)
	v_mfma_f32_16x16x32_bf16 v[60:63], v[148:151], v[212:215], v[60:63]
	v_mfma_f32_16x16x32_bf16 v[56:59], v[188:191], v[212:215], v[56:59]
	v_mfma_f32_16x16x32_bf16 v[44:47], v[148:151], v[220:223], v[44:47]
	v_mfma_f32_16x16x32_bf16 v[40:43], v[188:191], v[220:223], v[40:43]
	v_mfma_f32_16x16x32_bf16 v[28:31], v[148:151], v[228:231], v[28:31]
	v_mfma_f32_16x16x32_bf16 v[24:27], v[188:191], v[228:231], v[24:27]
	v_mfma_f32_16x16x32_bf16 v[12:15], v[148:151], v[236:239], v[12:15]
	v_mfma_f32_16x16x32_bf16 v[8:11], v[188:191], v[236:239], v[8:11]
	v_mfma_f32_16x16x32_bf16 v[60:63], v[184:187], v[216:219], v[60:63]
	v_mfma_f32_16x16x32_bf16 v[56:59], v[192:195], v[216:219], v[56:59]
	v_mfma_f32_16x16x32_bf16 v[44:47], v[184:187], v[224:227], v[44:47]
	v_mfma_f32_16x16x32_bf16 v[40:43], v[192:195], v[224:227], v[40:43]
	v_mfma_f32_16x16x32_bf16 v[28:31], v[184:187], v[232:235], v[28:31]
	v_mfma_f32_16x16x32_bf16 v[24:27], v[192:195], v[232:235], v[24:27]
	v_mfma_f32_16x16x32_bf16 v[12:15], v[184:187], v[240:243], v[12:15]
	v_mfma_f32_16x16x32_bf16 v[8:11], v[192:195], v[240:243], v[8:11]
	v_mfma_f32_16x16x32_bf16 v[52:55], v[196:199], v[212:215], v[52:55]
	v_mfma_f32_16x16x32_bf16 v[48:51], v[204:207], v[212:215], v[48:51]
	v_mfma_f32_16x16x32_bf16 v[36:39], v[196:199], v[220:223], v[36:39]
	v_mfma_f32_16x16x32_bf16 v[32:35], v[204:207], v[220:223], v[32:35]
	v_mfma_f32_16x16x32_bf16 v[20:23], v[196:199], v[228:231], v[20:23]
	v_mfma_f32_16x16x32_bf16 v[16:19], v[204:207], v[228:231], v[16:19]
	v_mfma_f32_16x16x32_bf16 v[4:7], v[196:199], v[236:239], v[4:7]
	v_mfma_f32_16x16x32_bf16 v[0:3], v[204:207], v[236:239], v[0:3]
	v_mfma_f32_16x16x32_bf16 v[52:55], v[200:203], v[216:219], v[52:55]
	v_mfma_f32_16x16x32_bf16 v[48:51], v[208:211], v[216:219], v[48:51]
	v_mfma_f32_16x16x32_bf16 v[36:39], v[200:203], v[224:227], v[36:39]
	v_mfma_f32_16x16x32_bf16 v[32:35], v[208:211], v[224:227], v[32:35]
	v_mfma_f32_16x16x32_bf16 v[20:23], v[200:203], v[232:235], v[20:23]
	v_mfma_f32_16x16x32_bf16 v[16:19], v[208:211], v[232:235], v[16:19]
	v_mfma_f32_16x16x32_bf16 v[4:7], v[200:203], v[240:243], v[4:7]
	v_mfma_f32_16x16x32_bf16 v[0:3], v[208:211], v[240:243], v[0:3]
	s_setprio 0
	s_barrier
	s_add_i32 s61, s61, 2
	s_add_u32 s54, s54, 0x100
	s_addc_u32 s55, s55, 0
	s_add_u32 s59, s59, 0x100
	s_addc_u32 s60, s60, 0
	s_cmp_gt_u32 s61, 61
	s_cbranch_scc0 .LBB0_146
	s_and_b64 vcc, exec, s[36:37]
	s_cbranch_vccz .LBB0_149
	s_barrier

.LBB0_183:
	s_add_u32 s4, s54, 0xfffc0080
	s_addc_u32 s5, s55, -1
	s_add_i32 s62, 0, 0x10000
	s_cmp_eq_u32 s61, 12
	s_cselect_b32 s57, s33, s5
	s_cselect_b32 s56, s49, s4
	v_add_u32_e32 v138, s62, v158
	s_cselect_b32 s5, s47, s60
	s_cselect_b32 s4, s58, s59
	s_add_i32 s64, 0, 0x14000
	ds_read_b128 v[148:151], v138
	ds_read_b128 v[152:155], v138 offset:1024
	ds_read_b128 v[162:165], v138 offset:2048
	ds_read_b128 v[166:169], v138 offset:3072
	v_add_u32_e32 v138, s64, v158
	ds_read_b128 v[170:173], v138
	ds_read_b128 v[184:187], v138 offset:1024
	ds_read_b128 v[188:191], v138 offset:2048
	ds_read_b128 v[192:195], v138 offset:3072
	v_lshl_add_u64 v[156:157], s[54:55], 0, v[144:145]
	s_add_i32 m0, s3, 0xc000
	ds_read_b128 v[196:199], v65
	ds_read_b128 v[200:203], v65 offset:1024
	ds_read_b128 v[204:207], v65 offset:2048
	ds_read_b128 v[208:211], v65 offset:3072
	ds_read_b128 v[212:215], v65 offset:4096
	ds_read_b128 v[216:219], v65 offset:5120
	ds_read_b128 v[220:223], v65 offset:6144
	ds_read_b128 v[224:227], v65 offset:7168
	global_load_lds_dwordx4 v[156:157], off
	v_lshl_add_u64 v[156:157], s[54:55], 0, v[146:147]
	s_add_i32 m0, s3, 0xe000
	s_nop 0
	global_load_lds_dwordx4 v[156:157], off
	s_waitcnt vmcnt(8)
	s_waitcnt lgkmcnt(0)
	s_barrier
	s_setprio 1
	s_waitcnt lgkmcnt(0)
	v_mfma_f32_16x16x32_bf16 v[126:129], v[148:151], v[196:199], v[126:129]
	v_mfma_f32_16x16x32_bf16 v[122:125], v[162:165], v[196:199], v[122:125]
	v_mfma_f32_16x16x32_bf16 v[110:113], v[148:151], v[204:207], v[110:113]
	v_mfma_f32_16x16x32_bf16 v[106:109], v[162:165], v[204:207], v[106:109]
	v_mfma_f32_16x16x32_bf16 v[94:97], v[148:151], v[212:215], v[94:97]
	v_mfma_f32_16x16x32_bf16 v[90:93], v[162:165], v[212:215], v[90:93]
	v_mfma_f32_16x16x32_bf16 v[78:81], v[148:151], v[220:223], v[78:81]
	v_mfma_f32_16x16x32_bf16 v[74:77], v[162:165], v[220:223], v[74:77]
	v_mfma_f32_16x16x32_bf16 v[126:129], v[152:155], v[200:203], v[126:129]
	v_mfma_f32_16x16x32_bf16 v[122:125], v[166:169], v[200:203], v[122:125]
	v_mfma_f32_16x16x32_bf16 v[110:113], v[152:155], v[208:211], v[110:113]
	v_mfma_f32_16x16x32_bf16 v[106:109], v[166:169], v[208:211], v[106:109]
	v_mfma_f32_16x16x32_bf16 v[94:97], v[152:155], v[216:219], v[94:97]
	v_mfma_f32_16x16x32_bf16 v[90:93], v[166:169], v[216:219], v[90:93]
	v_mfma_f32_16x16x32_bf16 v[78:81], v[152:155], v[224:227], v[78:81]
	v_mfma_f32_16x16x32_bf16 v[74:77], v[166:169], v[224:227], v[74:77]
	v_mfma_f32_16x16x32_bf16 v[118:121], v[170:173], v[196:199], v[118:121]
	v_mfma_f32_16x16x32_bf16 v[114:117], v[188:191], v[196:199], v[114:117]
	v_mfma_f32_16x16x32_bf16 v[102:105], v[170:173], v[204:207], v[102:105]
	v_mfma_f32_16x16x32_bf16 v[98:101], v[188:191], v[204:207], v[98:101]
	v_mfma_f32_16x16x32_bf16 v[86:89], v[170:173], v[212:215], v[86:89]
	v_mfma_f32_16x16x32_bf16 v[82:85], v[188:191], v[212:215], v[82:85]
	v_mfma_f32_16x16x32_bf16 v[70:73], v[170:173], v[220:223], v[70:73]
	v_mfma_f32_16x16x32_bf16 v[66:69], v[188:191], v[220:223], v[66:69]
	v_mfma_f32_16x16x32_bf16 v[118:121], v[184:187], v[200:203], v[118:121]
	v_mfma_f32_16x16x32_bf16 v[114:117], v[192:195], v[200:203], v[114:117]
	v_mfma_f32_16x16x32_bf16 v[102:105], v[184:187], v[208:211], v[102:105]
	v_mfma_f32_16x16x32_bf16 v[98:101], v[192:195], v[208:211], v[98:101]
	v_mfma_f32_16x16x32_bf16 v[86:89], v[184:187], v[216:219], v[86:89]
	v_mfma_f32_16x16x32_bf16 v[82:85], v[192:195], v[216:219], v[82:85]
	v_mfma_f32_16x16x32_bf16 v[70:73], v[184:187], v[224:227], v[70:73]
	v_mfma_f32_16x16x32_bf16 v[66:69], v[192:195], v[224:227], v[66:69]
	s_setprio 0
	s_barrier
	s_add_i32 s62, s62, s2
	v_lshl_add_u64 v[156:157], s[4:5], 0, v[134:135]
	s_mov_b32 m0, s62
	ds_read_b128 v[196:199], v65 offset:16384
	ds_read_b128 v[200:203], v65 offset:17408
	ds_read_b128 v[204:207], v65 offset:18432
	ds_read_b128 v[208:211], v65 offset:19456
	ds_read_b128 v[212:215], v65 offset:20480
	ds_read_b128 v[216:219], v65 offset:21504
	ds_read_b128 v[220:223], v65 offset:22528
	ds_read_b128 v[224:227], v65 offset:23552
	global_load_lds_dwordx4 v[156:157], off
	s_add_i32 m0, s62, 0x2000
	s_add_u32 s62, s4, 0x40000
	v_lshl_add_u64 v[174:175], s[4:5], 0, v[130:131]
	s_addc_u32 s63, s5, 0
	s_add_i32 s64, s64, s2
	global_load_lds_dwordx4 v[174:175], off
	v_lshl_add_u64 v[182:183], s[62:63], 0, v[134:135]
	s_mov_b32 m0, s64
	v_lshl_add_u64 v[228:229], s[56:57], 0, v[132:133]
	global_load_lds_dwordx4 v[182:183], off
	v_lshl_add_u64 v[182:183], s[62:63], 0, v[130:131]
	s_add_i32 m0, s64, 0x2000
	s_nop 0
	global_load_lds_dwordx4 v[182:183], off
	v_lshl_add_u64 v[182:183], s[56:57], 0, v[136:137]
	s_mov_b32 m0, s3
	s_nop 0
	global_load_lds_dwordx4 v[182:183], off
	s_mov_b32 m0, s10
	s_nop 0
	global_load_lds_dwordx4 v[228:229], off
	s_waitcnt vmcnt(8)
	s_waitcnt lgkmcnt(0)
	s_barrier
	s_setprio 1
	s_waitcnt lgkmcnt(0)
	v_mfma_f32_16x16x32_bf16 v[60:63], v[148:151], v[196:199], v[60:63]
	v_mfma_f32_16x16x32_bf16 v[56:59], v[162:165], v[196:199], v[56:59]
	v_mfma_f32_16x16x32_bf16 v[44:47], v[148:151], v[204:207], v[44:47]
	v_mfma_f32_16x16x32_bf16 v[40:43], v[162:165], v[204:207], v[40:43]
	v_mfma_f32_16x16x32_bf16 v[28:31], v[148:151], v[212:215], v[28:31]
	v_mfma_f32_16x16x32_bf16 v[24:27], v[162:165], v[212:215], v[24:27]
	v_mfma_f32_16x16x32_bf16 v[12:15], v[148:151], v[220:223], v[12:15]
	v_mfma_f32_16x16x32_bf16 v[8:11], v[162:165], v[220:223], v[8:11]
	v_mfma_f32_16x16x32_bf16 v[60:63], v[152:155], v[200:203], v[60:63]
	v_mfma_f32_16x16x32_bf16 v[56:59], v[166:169], v[200:203], v[56:59]
	v_mfma_f32_16x16x32_bf16 v[44:47], v[152:155], v[208:211], v[44:47]
	v_mfma_f32_16x16x32_bf16 v[40:43], v[166:169], v[208:211], v[40:43]
	v_mfma_f32_16x16x32_bf16 v[28:31], v[152:155], v[216:219], v[28:31]
	v_mfma_f32_16x16x32_bf16 v[24:27], v[166:169], v[216:219], v[24:27]
	v_mfma_f32_16x16x32_bf16 v[12:15], v[152:155], v[224:227], v[12:15]
	v_mfma_f32_16x16x32_bf16 v[8:11], v[166:169], v[224:227], v[8:11]
	v_mfma_f32_16x16x32_bf16 v[52:55], v[170:173], v[196:199], v[52:55]
	v_mfma_f32_16x16x32_bf16 v[48:51], v[188:191], v[196:199], v[48:51]
	v_mfma_f32_16x16x32_bf16 v[36:39], v[170:173], v[204:207], v[36:39]
	v_mfma_f32_16x16x32_bf16 v[32:35], v[188:191], v[204:207], v[32:35]
	v_mfma_f32_16x16x32_bf16 v[20:23], v[170:173], v[212:215], v[20:23]
	v_mfma_f32_16x16x32_bf16 v[16:19], v[188:191], v[212:215], v[16:19]
	v_mfma_f32_16x16x32_bf16 v[4:7], v[170:173], v[220:223], v[4:7]
	v_mfma_f32_16x16x32_bf16 v[0:3], v[188:191], v[220:223], v[0:3]
	v_mfma_f32_16x16x32_bf16 v[52:55], v[184:187], v[200:203], v[52:55]
	v_mfma_f32_16x16x32_bf16 v[48:51], v[192:195], v[200:203], v[48:51]
	v_mfma_f32_16x16x32_bf16 v[36:39], v[184:187], v[208:211], v[36:39]
	v_mfma_f32_16x16x32_bf16 v[32:35], v[192:195], v[208:211], v[32:35]
	v_mfma_f32_16x16x32_bf16 v[20:23], v[184:187], v[216:219], v[20:23]
	v_mfma_f32_16x16x32_bf16 v[16:19], v[192:195], v[216:219], v[16:19]
	v_mfma_f32_16x16x32_bf16 v[4:7], v[184:187], v[224:227], v[4:7]
	v_mfma_f32_16x16x32_bf16 v[0:3], v[192:195], v[224:227], v[0:3]
	s_setprio 0
	s_barrier
	s_add_i32 s62, 0, 0x18000
	v_add_u32_e32 v138, s62, v158
	s_add_i32 s63, 0, 0x1c000
	ds_read_b128 v[148:151], v138
	ds_read_b128 v[152:155], v138 offset:1024
	ds_read_b128 v[162:165], v138 offset:2048
	ds_read_b128 v[166:169], v138 offset:3072
	v_add_u32_e32 v138, s63, v158
	ds_read_b128 v[170:173], v138
	ds_read_b128 v[184:187], v138 offset:1024
	ds_read_b128 v[188:191], v138 offset:2048
	ds_read_b128 v[192:195], v138 offset:3072
	s_add_u32 s56, s56, 0x40000
	s_addc_u32 s57, s57, 0
	s_mov_b32 m0, s18
	v_lshl_add_u64 v[230:231], s[56:57], 0, v[136:137]
	ds_read_b128 v[196:199], v65 offset:32768
	ds_read_b128 v[200:203], v65 offset:33792
	ds_read_b128 v[204:207], v65 offset:34816
	ds_read_b128 v[208:211], v65 offset:35840
	ds_read_b128 v[212:215], v65 offset:36864
	ds_read_b128 v[216:219], v65 offset:37888
	ds_read_b128 v[220:223], v65 offset:38912
	ds_read_b128 v[224:227], v65 offset:39936
	global_load_lds_dwordx4 v[230:231], off
	v_lshl_add_u64 v[230:231], s[56:57], 0, v[132:133]
	s_mov_b32 m0, s19
	s_nop 0
	global_load_lds_dwordx4 v[230:231], off
	s_waitcnt vmcnt(8)
	s_waitcnt lgkmcnt(0)
	s_barrier
	s_setprio 1
	s_waitcnt lgkmcnt(0)
	v_mfma_f32_16x16x32_bf16 v[126:129], v[148:151], v[196:199], v[126:129]
	v_mfma_f32_16x16x32_bf16 v[122:125], v[162:165], v[196:199], v[122:125]
	v_mfma_f32_16x16x32_bf16 v[110:113], v[148:151], v[204:207], v[110:113]
	v_mfma_f32_16x16x32_bf16 v[106:109], v[162:165], v[204:207], v[106:109]
	v_mfma_f32_16x16x32_bf16 v[94:97], v[148:151], v[212:215], v[94:97]
	v_mfma_f32_16x16x32_bf16 v[90:93], v[162:165], v[212:215], v[90:93]
	v_mfma_f32_16x16x32_bf16 v[78:81], v[148:151], v[220:223], v[78:81]
	v_mfma_f32_16x16x32_bf16 v[74:77], v[162:165], v[220:223], v[74:77]
	v_mfma_f32_16x16x32_bf16 v[126:129], v[152:155], v[200:203], v[126:129]
	v_mfma_f32_16x16x32_bf16 v[122:125], v[166:169], v[200:203], v[122:125]
	v_mfma_f32_16x16x32_bf16 v[110:113], v[152:155], v[208:211], v[110:113]
	v_mfma_f32_16x16x32_bf16 v[106:109], v[166:169], v[208:211], v[106:109]
	v_mfma_f32_16x16x32_bf16 v[94:97], v[152:155], v[216:219], v[94:97]
	v_mfma_f32_16x16x32_bf16 v[90:93], v[166:169], v[216:219], v[90:93]
	v_mfma_f32_16x16x32_bf16 v[78:81], v[152:155], v[224:227], v[78:81]
	v_mfma_f32_16x16x32_bf16 v[74:77], v[166:169], v[224:227], v[74:77]
	v_mfma_f32_16x16x32_bf16 v[118:121], v[170:173], v[196:199], v[118:121]
	v_mfma_f32_16x16x32_bf16 v[114:117], v[188:191], v[196:199], v[114:117]
	v_mfma_f32_16x16x32_bf16 v[102:105], v[170:173], v[204:207], v[102:105]
	v_mfma_f32_16x16x32_bf16 v[98:101], v[188:191], v[204:207], v[98:101]
	v_mfma_f32_16x16x32_bf16 v[86:89], v[170:173], v[212:215], v[86:89]
	v_mfma_f32_16x16x32_bf16 v[82:85], v[188:191], v[212:215], v[82:85]
	v_mfma_f32_16x16x32_bf16 v[70:73], v[170:173], v[220:223], v[70:73]
	v_mfma_f32_16x16x32_bf16 v[66:69], v[188:191], v[220:223], v[66:69]
	v_mfma_f32_16x16x32_bf16 v[118:121], v[184:187], v[200:203], v[118:121]
	v_mfma_f32_16x16x32_bf16 v[114:117], v[192:195], v[200:203], v[114:117]
	v_mfma_f32_16x16x32_bf16 v[102:105], v[184:187], v[208:211], v[102:105]
	v_mfma_f32_16x16x32_bf16 v[98:101], v[192:195], v[208:211], v[98:101]
	v_mfma_f32_16x16x32_bf16 v[86:89], v[184:187], v[216:219], v[86:89]
	v_mfma_f32_16x16x32_bf16 v[82:85], v[192:195], v[216:219], v[82:85]
	v_mfma_f32_16x16x32_bf16 v[70:73], v[184:187], v[224:227], v[70:73]
	v_mfma_f32_16x16x32_bf16 v[66:69], v[192:195], v[224:227], v[66:69]
	s_setprio 0
	s_barrier
	s_add_i32 s56, s62, s2
	v_lshl_add_u64 v[156:157], v[156:157], 0, s[14:15]
	s_mov_b32 m0, s56
	ds_read_b128 v[196:199], v65 offset:49152
	ds_read_b128 v[200:203], v65 offset:50176
	ds_read_b128 v[204:207], v65 offset:51200
	ds_read_b128 v[208:211], v65 offset:52224
	ds_read_b128 v[212:215], v65 offset:53248
	ds_read_b128 v[216:219], v65 offset:54272
	ds_read_b128 v[220:223], v65 offset:55296
	ds_read_b128 v[224:227], v65 offset:56320
	global_load_lds_dwordx4 v[156:157], off
	s_add_i32 m0, s56, 0x2000
	s_add_u32 s4, s4, 0x40080
	v_lshl_add_u64 v[156:157], v[174:175], 0, s[14:15]
	s_addc_u32 s5, s5, 0
	s_add_i32 s56, s63, s2
	global_load_lds_dwordx4 v[156:157], off
	v_lshl_add_u64 v[156:157], s[4:5], 0, v[134:135]
	s_mov_b32 m0, s56
	s_nop 0
	global_load_lds_dwordx4 v[156:157], off
	v_lshl_add_u64 v[156:157], s[4:5], 0, v[130:131]
	s_add_i32 m0, s56, 0x2000
	s_nop 0
	global_load_lds_dwordx4 v[156:157], off
	v_lshl_add_u64 v[156:157], v[182:183], 0, s[14:15]
	s_mov_b32 m0, s21
	s_nop 0
	global_load_lds_dwordx4 v[156:157], off
	v_lshl_add_u64 v[156:157], v[228:229], 0, s[14:15]
	s_mov_b32 m0, s24
	s_nop 0
	global_load_lds_dwordx4 v[156:157], off
	s_waitcnt vmcnt(8)
	s_waitcnt lgkmcnt(0)
	s_barrier
	s_setprio 1
	s_waitcnt lgkmcnt(0)
	v_mfma_f32_16x16x32_bf16 v[60:63], v[148:151], v[196:199], v[60:63]
	v_mfma_f32_16x16x32_bf16 v[56:59], v[162:165], v[196:199], v[56:59]
	v_mfma_f32_16x16x32_bf16 v[44:47], v[148:151], v[204:207], v[44:47]
	v_mfma_f32_16x16x32_bf16 v[40:43], v[162:165], v[204:207], v[40:43]
	v_mfma_f32_16x16x32_bf16 v[28:31], v[148:151], v[212:215], v[28:31]
	v_mfma_f32_16x16x32_bf16 v[24:27], v[162:165], v[212:215], v[24:27]
	v_mfma_f32_16x16x32_bf16 v[12:15], v[148:151], v[220:223], v[12:15]
	v_mfma_f32_16x16x32_bf16 v[8:11], v[162:165], v[220:223], v[8:11]
	v_mfma_f32_16x16x32_bf16 v[60:63], v[152:155], v[200:203], v[60:63]
	v_mfma_f32_16x16x32_bf16 v[56:59], v[166:169], v[200:203], v[56:59]
	v_mfma_f32_16x16x32_bf16 v[44:47], v[152:155], v[208:211], v[44:47]
	v_mfma_f32_16x16x32_bf16 v[40:43], v[166:169], v[208:211], v[40:43]
	v_mfma_f32_16x16x32_bf16 v[28:31], v[152:155], v[216:219], v[28:31]
	v_mfma_f32_16x16x32_bf16 v[24:27], v[166:169], v[216:219], v[24:27]
	v_mfma_f32_16x16x32_bf16 v[12:15], v[152:155], v[224:227], v[12:15]
	v_mfma_f32_16x16x32_bf16 v[8:11], v[166:169], v[224:227], v[8:11]
	v_mfma_f32_16x16x32_bf16 v[52:55], v[170:173], v[196:199], v[52:55]
	v_mfma_f32_16x16x32_bf16 v[48:51], v[188:191], v[196:199], v[48:51]
	v_mfma_f32_16x16x32_bf16 v[36:39], v[170:173], v[204:207], v[36:39]
	v_mfma_f32_16x16x32_bf16 v[32:35], v[188:191], v[204:207], v[32:35]
	v_mfma_f32_16x16x32_bf16 v[20:23], v[170:173], v[212:215], v[20:23]
	v_mfma_f32_16x16x32_bf16 v[16:19], v[188:191], v[212:215], v[16:19]
	v_mfma_f32_16x16x32_bf16 v[4:7], v[170:173], v[220:223], v[4:7]
	v_mfma_f32_16x16x32_bf16 v[0:3], v[188:191], v[220:223], v[0:3]
	v_mfma_f32_16x16x32_bf16 v[52:55], v[184:187], v[200:203], v[52:55]
	v_mfma_f32_16x16x32_bf16 v[48:51], v[192:195], v[200:203], v[48:51]
	v_mfma_f32_16x16x32_bf16 v[36:39], v[184:187], v[208:211], v[36:39]
	v_mfma_f32_16x16x32_bf16 v[32:35], v[192:195], v[208:211], v[32:35]
	v_mfma_f32_16x16x32_bf16 v[20:23], v[184:187], v[216:219], v[20:23]
	v_mfma_f32_16x16x32_bf16 v[16:19], v[192:195], v[216:219], v[16:19]
	v_mfma_f32_16x16x32_bf16 v[4:7], v[184:187], v[224:227], v[4:7]
	v_mfma_f32_16x16x32_bf16 v[0:3], v[192:195], v[224:227], v[0:3]
	s_setprio 0
	s_barrier
	s_add_i32 s61, s61, 2
	s_add_u32 s54, s54, 0x100
	s_addc_u32 s55, s55, 0
	s_add_u32 s59, s59, 0x100
	s_addc_u32 s60, s60, 0
	s_cmp_gt_u32 s61, 13
	s_cbranch_scc0 .LBB0_183
	s_and_b64 vcc, exec, s[44:45]
	s_cbranch_vccz .LBB0_186
	s_barrier

.LBB0_224:
	s_add_u32 s4, s50, 0xfffc0080
	s_addc_u32 s5, s51, -1
	s_add_i32 s57, 0, 0x10000
	s_cmp_eq_u32 s56, 12
	s_cselect_b32 s53, s29, s5
	s_cselect_b32 s52, s33, s4
	v_add_u32_e32 v138, s57, v171
	s_cselect_b32 s5, s43, s55
	s_cselect_b32 s4, s45, s54
	s_add_i32 s60, 0, 0x14000
	ds_read_b128 v[146:149], v138
	ds_read_b128 v[184:187], v138 offset:1024
	ds_read_b128 v[188:191], v138 offset:2048
	ds_read_b128 v[192:195], v138 offset:3072
	v_add_u32_e32 v138, s60, v171
	ds_read_b128 v[196:199], v138
	ds_read_b128 v[200:203], v138 offset:1024
	ds_read_b128 v[204:207], v138 offset:2048
	ds_read_b128 v[208:211], v138 offset:3072
	v_lshl_add_u64 v[174:175], s[50:51], 0, v[142:143]
	s_add_i32 m0, s3, 0xc000
	ds_read_b128 v[212:215], v173
	ds_read_b128 v[216:219], v173 offset:1024
	ds_read_b128 v[220:223], v173 offset:2048
	ds_read_b128 v[224:227], v173 offset:3072
	ds_read_b128 v[228:231], v173 offset:4096
	ds_read_b128 v[232:235], v173 offset:5120
	ds_read_b128 v[236:239], v173 offset:6144
	ds_read_b128 v[240:243], v173 offset:7168
	global_load_lds_dwordx4 v[174:175], off
	v_lshl_add_u64 v[174:175], s[50:51], 0, v[144:145]
	s_add_i32 m0, s3, 0xe000
	s_nop 0
	global_load_lds_dwordx4 v[174:175], off
	s_waitcnt vmcnt(8)
	s_waitcnt lgkmcnt(0)
	s_barrier
	s_setprio 1
	s_waitcnt lgkmcnt(0)
	v_mfma_f32_16x16x32_bf16 v[126:129], v[146:149], v[212:215], v[126:129]
	v_mfma_f32_16x16x32_bf16 v[122:125], v[188:191], v[212:215], v[122:125]
	v_mfma_f32_16x16x32_bf16 v[114:117], v[146:149], v[220:223], v[114:117]
	v_mfma_f32_16x16x32_bf16 v[106:109], v[188:191], v[220:223], v[106:109]
	v_mfma_f32_16x16x32_bf16 v[98:101], v[146:149], v[228:231], v[98:101]
	v_mfma_f32_16x16x32_bf16 v[90:93], v[188:191], v[228:231], v[90:93]
	v_mfma_f32_16x16x32_bf16 v[82:85], v[146:149], v[236:239], v[82:85]
	v_mfma_f32_16x16x32_bf16 v[74:77], v[188:191], v[236:239], v[74:77]
	v_mfma_f32_16x16x32_bf16 v[126:129], v[184:187], v[216:219], v[126:129]
	v_mfma_f32_16x16x32_bf16 v[122:125], v[192:195], v[216:219], v[122:125]
	v_mfma_f32_16x16x32_bf16 v[114:117], v[184:187], v[224:227], v[114:117]
	v_mfma_f32_16x16x32_bf16 v[106:109], v[192:195], v[224:227], v[106:109]
	v_mfma_f32_16x16x32_bf16 v[98:101], v[184:187], v[232:235], v[98:101]
	v_mfma_f32_16x16x32_bf16 v[90:93], v[192:195], v[232:235], v[90:93]
	v_mfma_f32_16x16x32_bf16 v[82:85], v[184:187], v[240:243], v[82:85]
	v_mfma_f32_16x16x32_bf16 v[74:77], v[192:195], v[240:243], v[74:77]
	v_mfma_f32_16x16x32_bf16 v[118:121], v[196:199], v[212:215], v[118:121]
	v_mfma_f32_16x16x32_bf16 v[110:113], v[204:207], v[212:215], v[110:113]
	v_mfma_f32_16x16x32_bf16 v[102:105], v[196:199], v[220:223], v[102:105]
	v_mfma_f32_16x16x32_bf16 v[94:97], v[204:207], v[220:223], v[94:97]
	v_mfma_f32_16x16x32_bf16 v[86:89], v[196:199], v[228:231], v[86:89]
	v_mfma_f32_16x16x32_bf16 v[78:81], v[204:207], v[228:231], v[78:81]
	v_mfma_f32_16x16x32_bf16 v[70:73], v[196:199], v[236:239], v[70:73]
	v_mfma_f32_16x16x32_bf16 v[66:69], v[204:207], v[236:239], v[66:69]
	v_mfma_f32_16x16x32_bf16 v[118:121], v[200:203], v[216:219], v[118:121]
	v_mfma_f32_16x16x32_bf16 v[110:113], v[208:211], v[216:219], v[110:113]
	v_mfma_f32_16x16x32_bf16 v[102:105], v[200:203], v[224:227], v[102:105]
	v_mfma_f32_16x16x32_bf16 v[94:97], v[208:211], v[224:227], v[94:97]
	v_mfma_f32_16x16x32_bf16 v[86:89], v[200:203], v[232:235], v[86:89]
	v_mfma_f32_16x16x32_bf16 v[78:81], v[208:211], v[232:235], v[78:81]
	v_mfma_f32_16x16x32_bf16 v[70:73], v[200:203], v[240:243], v[70:73]
	v_mfma_f32_16x16x32_bf16 v[66:69], v[208:211], v[240:243], v[66:69]
	s_setprio 0
	s_barrier
	s_add_i32 s57, s57, s2
	v_lshl_add_u64 v[174:175], s[4:5], 0, v[134:135]
	s_mov_b32 m0, s57
	ds_read_b128 v[212:215], v173 offset:16384
	ds_read_b128 v[216:219], v173 offset:17408
	ds_read_b128 v[220:223], v173 offset:18432
	ds_read_b128 v[224:227], v173 offset:19456
	ds_read_b128 v[228:231], v173 offset:20480
	ds_read_b128 v[232:235], v173 offset:21504
	ds_read_b128 v[236:239], v173 offset:22528
	ds_read_b128 v[240:243], v173 offset:23552
	global_load_lds_dwordx4 v[174:175], off
	s_add_i32 m0, s57, 0x2000
	s_add_u32 s58, s4, 0x40000
	v_lshl_add_u64 v[182:183], s[4:5], 0, v[130:131]
	s_addc_u32 s59, s5, 0
	s_add_i32 s57, s60, s2
	global_load_lds_dwordx4 v[182:183], off
	v_lshl_add_u64 v[244:245], s[58:59], 0, v[134:135]
	s_mov_b32 m0, s57
	v_lshl_add_u64 v[246:247], s[52:53], 0, v[132:133]
	global_load_lds_dwordx4 v[244:245], off
	v_lshl_add_u64 v[244:245], s[58:59], 0, v[130:131]
	s_add_i32 m0, s57, 0x2000
	s_nop 0
	global_load_lds_dwordx4 v[244:245], off
	v_lshl_add_u64 v[244:245], s[52:53], 0, v[136:137]
	s_mov_b32 m0, s3
	s_nop 0
	global_load_lds_dwordx4 v[244:245], off
	s_mov_b32 m0, s10
	s_nop 0
	global_load_lds_dwordx4 v[246:247], off
	s_waitcnt vmcnt(8)
	s_waitcnt lgkmcnt(0)
	s_barrier
	s_setprio 1
	s_waitcnt lgkmcnt(0)
	v_mfma_f32_16x16x32_bf16 v[60:63], v[146:149], v[212:215], v[60:63]
	v_mfma_f32_16x16x32_bf16 v[56:59], v[188:191], v[212:215], v[56:59]
	v_mfma_f32_16x16x32_bf16 v[48:51], v[146:149], v[220:223], v[48:51]
	v_mfma_f32_16x16x32_bf16 v[40:43], v[188:191], v[220:223], v[40:43]
	v_mfma_f32_16x16x32_bf16 v[32:35], v[146:149], v[228:231], v[32:35]
	v_mfma_f32_16x16x32_bf16 v[24:27], v[188:191], v[228:231], v[24:27]
	v_mfma_f32_16x16x32_bf16 v[16:19], v[146:149], v[236:239], v[16:19]
	v_mfma_f32_16x16x32_bf16 v[8:11], v[188:191], v[236:239], v[8:11]
	v_mfma_f32_16x16x32_bf16 v[60:63], v[184:187], v[216:219], v[60:63]
	v_mfma_f32_16x16x32_bf16 v[56:59], v[192:195], v[216:219], v[56:59]
	v_mfma_f32_16x16x32_bf16 v[48:51], v[184:187], v[224:227], v[48:51]
	v_mfma_f32_16x16x32_bf16 v[40:43], v[192:195], v[224:227], v[40:43]
	v_mfma_f32_16x16x32_bf16 v[32:35], v[184:187], v[232:235], v[32:35]
	v_mfma_f32_16x16x32_bf16 v[24:27], v[192:195], v[232:235], v[24:27]
	v_mfma_f32_16x16x32_bf16 v[16:19], v[184:187], v[240:243], v[16:19]
	v_mfma_f32_16x16x32_bf16 v[8:11], v[192:195], v[240:243], v[8:11]
	v_mfma_f32_16x16x32_bf16 v[52:55], v[196:199], v[212:215], v[52:55]
	v_mfma_f32_16x16x32_bf16 v[44:47], v[204:207], v[212:215], v[44:47]
	v_mfma_f32_16x16x32_bf16 v[36:39], v[196:199], v[220:223], v[36:39]
	v_mfma_f32_16x16x32_bf16 v[28:31], v[204:207], v[220:223], v[28:31]
	v_mfma_f32_16x16x32_bf16 v[20:23], v[196:199], v[228:231], v[20:23]
	v_mfma_f32_16x16x32_bf16 v[12:15], v[204:207], v[228:231], v[12:15]
	v_mfma_f32_16x16x32_bf16 v[4:7], v[196:199], v[236:239], v[4:7]
	v_mfma_f32_16x16x32_bf16 v[0:3], v[204:207], v[236:239], v[0:3]
	v_mfma_f32_16x16x32_bf16 v[52:55], v[200:203], v[216:219], v[52:55]
	v_mfma_f32_16x16x32_bf16 v[44:47], v[208:211], v[216:219], v[44:47]
	v_mfma_f32_16x16x32_bf16 v[36:39], v[200:203], v[224:227], v[36:39]
	v_mfma_f32_16x16x32_bf16 v[28:31], v[208:211], v[224:227], v[28:31]
	v_mfma_f32_16x16x32_bf16 v[20:23], v[200:203], v[232:235], v[20:23]
	v_mfma_f32_16x16x32_bf16 v[12:15], v[208:211], v[232:235], v[12:15]
	v_mfma_f32_16x16x32_bf16 v[4:7], v[200:203], v[240:243], v[4:7]
	v_mfma_f32_16x16x32_bf16 v[0:3], v[208:211], v[240:243], v[0:3]
	s_setprio 0
	s_barrier
	s_add_i32 s57, 0, 0x18000
	v_add_u32_e32 v138, s57, v171
	s_add_i32 s58, 0, 0x1c000
	ds_read_b128 v[146:149], v138
	ds_read_b128 v[184:187], v138 offset:1024
	ds_read_b128 v[188:191], v138 offset:2048
	ds_read_b128 v[192:195], v138 offset:3072
	v_add_u32_e32 v138, s58, v171
	ds_read_b128 v[196:199], v138
	ds_read_b128 v[200:203], v138 offset:1024
	ds_read_b128 v[204:207], v138 offset:2048
	ds_read_b128 v[208:211], v138 offset:3072
	s_add_u32 s52, s52, 0x40000
	s_addc_u32 s53, s53, 0
	s_mov_b32 m0, s18
	v_lshl_add_u64 v[248:249], s[52:53], 0, v[136:137]
	ds_read_b128 v[212:215], v173 offset:32768
	ds_read_b128 v[216:219], v173 offset:33792
	ds_read_b128 v[220:223], v173 offset:34816
	ds_read_b128 v[224:227], v173 offset:35840
	ds_read_b128 v[228:231], v173 offset:36864
	ds_read_b128 v[232:235], v173 offset:37888
	ds_read_b128 v[236:239], v173 offset:38912
	ds_read_b128 v[240:243], v173 offset:39936
	global_load_lds_dwordx4 v[248:249], off
	v_lshl_add_u64 v[248:249], s[52:53], 0, v[132:133]
	s_mov_b32 m0, s19
	s_nop 0
	global_load_lds_dwordx4 v[248:249], off
	s_waitcnt vmcnt(8)
	s_waitcnt lgkmcnt(0)
	s_barrier
	s_setprio 1
	s_waitcnt lgkmcnt(0)
	v_mfma_f32_16x16x32_bf16 v[126:129], v[146:149], v[212:215], v[126:129]
	v_mfma_f32_16x16x32_bf16 v[122:125], v[188:191], v[212:215], v[122:125]
	v_mfma_f32_16x16x32_bf16 v[114:117], v[146:149], v[220:223], v[114:117]
	v_mfma_f32_16x16x32_bf16 v[106:109], v[188:191], v[220:223], v[106:109]
	v_mfma_f32_16x16x32_bf16 v[98:101], v[146:149], v[228:231], v[98:101]
	v_mfma_f32_16x16x32_bf16 v[90:93], v[188:191], v[228:231], v[90:93]
	v_mfma_f32_16x16x32_bf16 v[82:85], v[146:149], v[236:239], v[82:85]
	v_mfma_f32_16x16x32_bf16 v[74:77], v[188:191], v[236:239], v[74:77]
	v_mfma_f32_16x16x32_bf16 v[126:129], v[184:187], v[216:219], v[126:129]
	v_mfma_f32_16x16x32_bf16 v[122:125], v[192:195], v[216:219], v[122:125]
	v_mfma_f32_16x16x32_bf16 v[114:117], v[184:187], v[224:227], v[114:117]
	v_mfma_f32_16x16x32_bf16 v[106:109], v[192:195], v[224:227], v[106:109]
	v_mfma_f32_16x16x32_bf16 v[98:101], v[184:187], v[232:235], v[98:101]
	v_mfma_f32_16x16x32_bf16 v[90:93], v[192:195], v[232:235], v[90:93]
	v_mfma_f32_16x16x32_bf16 v[82:85], v[184:187], v[240:243], v[82:85]
	v_mfma_f32_16x16x32_bf16 v[74:77], v[192:195], v[240:243], v[74:77]
	v_mfma_f32_16x16x32_bf16 v[118:121], v[196:199], v[212:215], v[118:121]
	v_mfma_f32_16x16x32_bf16 v[110:113], v[204:207], v[212:215], v[110:113]
	v_mfma_f32_16x16x32_bf16 v[102:105], v[196:199], v[220:223], v[102:105]
	v_mfma_f32_16x16x32_bf16 v[94:97], v[204:207], v[220:223], v[94:97]
	v_mfma_f32_16x16x32_bf16 v[86:89], v[196:199], v[228:231], v[86:89]
	v_mfma_f32_16x16x32_bf16 v[78:81], v[204:207], v[228:231], v[78:81]
	v_mfma_f32_16x16x32_bf16 v[70:73], v[196:199], v[236:239], v[70:73]
	v_mfma_f32_16x16x32_bf16 v[66:69], v[204:207], v[236:239], v[66:69]
	v_mfma_f32_16x16x32_bf16 v[118:121], v[200:203], v[216:219], v[118:121]
	v_mfma_f32_16x16x32_bf16 v[110:113], v[208:211], v[216:219], v[110:113]
	v_mfma_f32_16x16x32_bf16 v[102:105], v[200:203], v[224:227], v[102:105]
	v_mfma_f32_16x16x32_bf16 v[94:97], v[208:211], v[224:227], v[94:97]
	v_mfma_f32_16x16x32_bf16 v[86:89], v[200:203], v[232:235], v[86:89]
	v_mfma_f32_16x16x32_bf16 v[78:81], v[208:211], v[232:235], v[78:81]
	v_mfma_f32_16x16x32_bf16 v[70:73], v[200:203], v[240:243], v[70:73]
	v_mfma_f32_16x16x32_bf16 v[66:69], v[208:211], v[240:243], v[66:69]
	s_setprio 0
	s_barrier
	s_add_i32 s52, s57, s2
	v_lshl_add_u64 v[174:175], v[174:175], 0, s[14:15]
	s_mov_b32 m0, s52
	ds_read_b128 v[212:215], v173 offset:49152
	ds_read_b128 v[216:219], v173 offset:50176
	ds_read_b128 v[220:223], v173 offset:51200
	ds_read_b128 v[224:227], v173 offset:52224
	ds_read_b128 v[228:231], v173 offset:53248
	ds_read_b128 v[232:235], v173 offset:54272
	ds_read_b128 v[236:239], v173 offset:55296
	ds_read_b128 v[240:243], v173 offset:56320
	global_load_lds_dwordx4 v[174:175], off
	s_add_i32 m0, s52, 0x2000
	s_add_u32 s4, s4, 0x40080
	v_lshl_add_u64 v[174:175], v[182:183], 0, s[14:15]
	s_addc_u32 s5, s5, 0
	s_add_i32 s52, s58, s2
	global_load_lds_dwordx4 v[174:175], off
	v_lshl_add_u64 v[174:175], s[4:5], 0, v[134:135]
	s_mov_b32 m0, s52
	s_nop 0
	global_load_lds_dwordx4 v[174:175], off
	v_lshl_add_u64 v[174:175], s[4:5], 0, v[130:131]
	s_add_i32 m0, s52, 0x2000
	s_nop 0
	global_load_lds_dwordx4 v[174:175], off
	v_lshl_add_u64 v[174:175], v[244:245], 0, s[14:15]
	s_mov_b32 m0, s20
	s_nop 0
	global_load_lds_dwordx4 v[174:175], off
	v_lshl_add_u64 v[174:175], v[246:247], 0, s[14:15]
	s_mov_b32 m0, s21
	s_nop 0
	global_load_lds_dwordx4 v[174:175], off
	s_waitcnt vmcnt(8)
	s_waitcnt lgkmcnt(0)
	s_barrier
	s_setprio 1
	s_waitcnt lgkmcnt(0)
	v_mfma_f32_16x16x32_bf16 v[60:63], v[146:149], v[212:215], v[60:63]
	v_mfma_f32_16x16x32_bf16 v[56:59], v[188:191], v[212:215], v[56:59]
	v_mfma_f32_16x16x32_bf16 v[48:51], v[146:149], v[220:223], v[48:51]
	v_mfma_f32_16x16x32_bf16 v[40:43], v[188:191], v[220:223], v[40:43]
	v_mfma_f32_16x16x32_bf16 v[32:35], v[146:149], v[228:231], v[32:35]
	v_mfma_f32_16x16x32_bf16 v[24:27], v[188:191], v[228:231], v[24:27]
	v_mfma_f32_16x16x32_bf16 v[16:19], v[146:149], v[236:239], v[16:19]
	v_mfma_f32_16x16x32_bf16 v[8:11], v[188:191], v[236:239], v[8:11]
	v_mfma_f32_16x16x32_bf16 v[60:63], v[184:187], v[216:219], v[60:63]
	v_mfma_f32_16x16x32_bf16 v[56:59], v[192:195], v[216:219], v[56:59]
	v_mfma_f32_16x16x32_bf16 v[48:51], v[184:187], v[224:227], v[48:51]
	v_mfma_f32_16x16x32_bf16 v[40:43], v[192:195], v[224:227], v[40:43]
	v_mfma_f32_16x16x32_bf16 v[32:35], v[184:187], v[232:235], v[32:35]
	v_mfma_f32_16x16x32_bf16 v[24:27], v[192:195], v[232:235], v[24:27]
	v_mfma_f32_16x16x32_bf16 v[16:19], v[184:187], v[240:243], v[16:19]
	v_mfma_f32_16x16x32_bf16 v[8:11], v[192:195], v[240:243], v[8:11]
	v_mfma_f32_16x16x32_bf16 v[52:55], v[196:199], v[212:215], v[52:55]
	v_mfma_f32_16x16x32_bf16 v[44:47], v[204:207], v[212:215], v[44:47]
	v_mfma_f32_16x16x32_bf16 v[36:39], v[196:199], v[220:223], v[36:39]
	v_mfma_f32_16x16x32_bf16 v[28:31], v[204:207], v[220:223], v[28:31]
	v_mfma_f32_16x16x32_bf16 v[20:23], v[196:199], v[228:231], v[20:23]
	v_mfma_f32_16x16x32_bf16 v[12:15], v[204:207], v[228:231], v[12:15]
	v_mfma_f32_16x16x32_bf16 v[4:7], v[196:199], v[236:239], v[4:7]
	v_mfma_f32_16x16x32_bf16 v[0:3], v[204:207], v[236:239], v[0:3]
	v_mfma_f32_16x16x32_bf16 v[52:55], v[200:203], v[216:219], v[52:55]
	v_mfma_f32_16x16x32_bf16 v[44:47], v[208:211], v[216:219], v[44:47]
	v_mfma_f32_16x16x32_bf16 v[36:39], v[200:203], v[224:227], v[36:39]
	v_mfma_f32_16x16x32_bf16 v[28:31], v[208:211], v[224:227], v[28:31]
	v_mfma_f32_16x16x32_bf16 v[20:23], v[200:203], v[232:235], v[20:23]
	v_mfma_f32_16x16x32_bf16 v[12:15], v[208:211], v[232:235], v[12:15]
	v_mfma_f32_16x16x32_bf16 v[4:7], v[200:203], v[240:243], v[4:7]
	v_mfma_f32_16x16x32_bf16 v[0:3], v[208:211], v[240:243], v[0:3]
	s_setprio 0
	s_barrier
	s_add_i32 s56, s56, 2
	s_add_u32 s50, s50, 0x100
	s_addc_u32 s51, s51, 0
	s_add_u32 s54, s54, 0x100
	s_addc_u32 s55, s55, 0
	s_cmp_gt_u32 s56, 13
	s_cbranch_scc0 .LBB0_224
	s_and_b64 vcc, exec, s[36:37]
	s_cbranch_vccz .LBB0_227
	s_barrier

.LBB0_244:
	s_add_u32 s4, s36, 0xfffe0080
	s_addc_u32 s5, s37, -1
	s_add_i32 s33, 0, 0x10000
	s_cmp_eq_u32 s29, 4
	s_cselect_b32 s51, s18, s5
	s_cselect_b32 s50, s19, s4
	v_add_u32_e32 v138, s33, v150
	s_cselect_b32 s5, s20, s25
	s_cselect_b32 s4, s21, s24
	s_add_i32 s43, 0, 0x14000
	ds_read_b128 v[146:149], v138
	ds_read_b128 v[154:157], v138 offset:1024
	ds_read_b128 v[158:161], v138 offset:2048
	ds_read_b128 v[162:165], v138 offset:3072
	v_add_u32_e32 v138, s43, v150
	ds_read_b128 v[166:169], v138
	s_waitcnt vmcnt(8)
	ds_read_b128 v[170:173], v138 offset:1024
	ds_read_b128 v[184:187], v138 offset:2048
	ds_read_b128 v[188:191], v138 offset:3072
	v_lshl_add_u64 v[174:175], s[36:37], 0, v[142:143]
	s_add_i32 m0, s53, 0xc000
	ds_read_b128 v[192:195], v152
	ds_read_b128 v[196:199], v152 offset:1024
	ds_read_b128 v[200:203], v152 offset:2048
	ds_read_b128 v[204:207], v152 offset:3072
	ds_read_b128 v[208:211], v152 offset:4096
	ds_read_b128 v[212:215], v152 offset:5120
	ds_read_b128 v[216:219], v152 offset:6144
	ds_read_b128 v[220:223], v152 offset:7168
	global_load_lds_dwordx4 v[174:175], off
	v_lshl_add_u64 v[174:175], s[36:37], 0, v[144:145]
	s_add_i32 m0, s53, 0xe000
	s_nop 0
	global_load_lds_dwordx4 v[174:175], off
	s_waitcnt vmcnt(8)
	s_waitcnt lgkmcnt(0)
	s_barrier
	s_setprio 1
	s_waitcnt lgkmcnt(0)
	v_mfma_f32_16x16x32_bf16 v[126:129], v[146:149], v[192:195], v[126:129]
	v_mfma_f32_16x16x32_bf16 v[122:125], v[158:161], v[192:195], v[122:125]
	v_mfma_f32_16x16x32_bf16 v[110:113], v[146:149], v[200:203], v[110:113]
	v_mfma_f32_16x16x32_bf16 v[106:109], v[158:161], v[200:203], v[106:109]
	v_mfma_f32_16x16x32_bf16 v[94:97], v[146:149], v[208:211], v[94:97]
	v_mfma_f32_16x16x32_bf16 v[90:93], v[158:161], v[208:211], v[90:93]
	v_mfma_f32_16x16x32_bf16 v[78:81], v[146:149], v[216:219], v[78:81]
	v_mfma_f32_16x16x32_bf16 v[74:77], v[158:161], v[216:219], v[74:77]
	v_mfma_f32_16x16x32_bf16 v[126:129], v[154:157], v[196:199], v[126:129]
	v_mfma_f32_16x16x32_bf16 v[122:125], v[162:165], v[196:199], v[122:125]
	v_mfma_f32_16x16x32_bf16 v[110:113], v[154:157], v[204:207], v[110:113]
	v_mfma_f32_16x16x32_bf16 v[106:109], v[162:165], v[204:207], v[106:109]
	v_mfma_f32_16x16x32_bf16 v[94:97], v[154:157], v[212:215], v[94:97]
	v_mfma_f32_16x16x32_bf16 v[90:93], v[162:165], v[212:215], v[90:93]
	v_mfma_f32_16x16x32_bf16 v[78:81], v[154:157], v[220:223], v[78:81]
	v_mfma_f32_16x16x32_bf16 v[74:77], v[162:165], v[220:223], v[74:77]
	v_mfma_f32_16x16x32_bf16 v[118:121], v[166:169], v[192:195], v[118:121]
	v_mfma_f32_16x16x32_bf16 v[114:117], v[184:187], v[192:195], v[114:117]
	v_mfma_f32_16x16x32_bf16 v[102:105], v[166:169], v[200:203], v[102:105]
	v_mfma_f32_16x16x32_bf16 v[98:101], v[184:187], v[200:203], v[98:101]
	v_mfma_f32_16x16x32_bf16 v[86:89], v[166:169], v[208:211], v[86:89]
	v_mfma_f32_16x16x32_bf16 v[82:85], v[184:187], v[208:211], v[82:85]
	v_mfma_f32_16x16x32_bf16 v[70:73], v[166:169], v[216:219], v[70:73]
	v_mfma_f32_16x16x32_bf16 v[66:69], v[184:187], v[216:219], v[66:69]
	v_mfma_f32_16x16x32_bf16 v[118:121], v[170:173], v[196:199], v[118:121]
	v_mfma_f32_16x16x32_bf16 v[114:117], v[188:191], v[196:199], v[114:117]
	v_mfma_f32_16x16x32_bf16 v[102:105], v[170:173], v[204:207], v[102:105]
	v_mfma_f32_16x16x32_bf16 v[98:101], v[188:191], v[204:207], v[98:101]
	v_mfma_f32_16x16x32_bf16 v[86:89], v[170:173], v[212:215], v[86:89]
	v_mfma_f32_16x16x32_bf16 v[82:85], v[188:191], v[212:215], v[82:85]
	v_mfma_f32_16x16x32_bf16 v[70:73], v[170:173], v[220:223], v[70:73]
	v_mfma_f32_16x16x32_bf16 v[66:69], v[188:191], v[220:223], v[66:69]
	s_setprio 0
	s_barrier
	s_add_i32 s33, s33, s52
	v_lshl_add_u64 v[174:175], s[4:5], 0, v[134:135]
	s_mov_b32 m0, s33
	ds_read_b128 v[192:195], v152 offset:16384
	ds_read_b128 v[196:199], v152 offset:17408
	ds_read_b128 v[200:203], v152 offset:18432
	ds_read_b128 v[204:207], v152 offset:19456
	ds_read_b128 v[208:211], v152 offset:20480
	ds_read_b128 v[212:215], v152 offset:21504
	ds_read_b128 v[216:219], v152 offset:22528
	ds_read_b128 v[220:223], v152 offset:23552
	global_load_lds_dwordx4 v[174:175], off
	s_add_i32 m0, s33, 0x2000
	s_add_u32 s58, s4, 0x20000
	v_lshl_add_u64 v[182:183], s[4:5], 0, v[130:131]
	s_addc_u32 s59, s5, 0
	s_add_i32 s33, s43, s52
	global_load_lds_dwordx4 v[182:183], off
	v_lshl_add_u64 v[224:225], s[58:59], 0, v[134:135]
	s_mov_b32 m0, s33
	v_lshl_add_u64 v[226:227], s[50:51], 0, v[132:133]
	global_load_lds_dwordx4 v[224:225], off
	v_lshl_add_u64 v[224:225], s[58:59], 0, v[130:131]
	s_add_i32 m0, s33, 0x2000
	s_nop 0
	global_load_lds_dwordx4 v[224:225], off
	v_lshl_add_u64 v[224:225], s[50:51], 0, v[136:137]
	s_mov_b32 m0, s53
	s_nop 0
	global_load_lds_dwordx4 v[224:225], off
	s_mov_b32 m0, s54
	s_nop 0
	global_load_lds_dwordx4 v[226:227], off
	s_waitcnt vmcnt(8)
	s_waitcnt lgkmcnt(0)
	s_barrier
	s_setprio 1
	s_waitcnt lgkmcnt(0)
	v_mfma_f32_16x16x32_bf16 v[60:63], v[146:149], v[192:195], v[60:63]
	v_mfma_f32_16x16x32_bf16 v[56:59], v[158:161], v[192:195], v[56:59]
	v_mfma_f32_16x16x32_bf16 v[44:47], v[146:149], v[200:203], v[44:47]
	v_mfma_f32_16x16x32_bf16 v[40:43], v[158:161], v[200:203], v[40:43]
	v_mfma_f32_16x16x32_bf16 v[28:31], v[146:149], v[208:211], v[28:31]
	v_mfma_f32_16x16x32_bf16 v[24:27], v[158:161], v[208:211], v[24:27]
	v_mfma_f32_16x16x32_bf16 v[12:15], v[146:149], v[216:219], v[12:15]
	v_mfma_f32_16x16x32_bf16 v[8:11], v[158:161], v[216:219], v[8:11]
	v_mfma_f32_16x16x32_bf16 v[60:63], v[154:157], v[196:199], v[60:63]
	v_mfma_f32_16x16x32_bf16 v[56:59], v[162:165], v[196:199], v[56:59]
	v_mfma_f32_16x16x32_bf16 v[44:47], v[154:157], v[204:207], v[44:47]
	v_mfma_f32_16x16x32_bf16 v[40:43], v[162:165], v[204:207], v[40:43]
	v_mfma_f32_16x16x32_bf16 v[28:31], v[154:157], v[212:215], v[28:31]
	v_mfma_f32_16x16x32_bf16 v[24:27], v[162:165], v[212:215], v[24:27]
	v_mfma_f32_16x16x32_bf16 v[12:15], v[154:157], v[220:223], v[12:15]
	v_mfma_f32_16x16x32_bf16 v[8:11], v[162:165], v[220:223], v[8:11]
	v_mfma_f32_16x16x32_bf16 v[52:55], v[166:169], v[192:195], v[52:55]
	v_mfma_f32_16x16x32_bf16 v[48:51], v[184:187], v[192:195], v[48:51]
	v_mfma_f32_16x16x32_bf16 v[36:39], v[166:169], v[200:203], v[36:39]
	v_mfma_f32_16x16x32_bf16 v[32:35], v[184:187], v[200:203], v[32:35]
	v_mfma_f32_16x16x32_bf16 v[20:23], v[166:169], v[208:211], v[20:23]
	v_mfma_f32_16x16x32_bf16 v[16:19], v[184:187], v[208:211], v[16:19]
	v_mfma_f32_16x16x32_bf16 v[4:7], v[166:169], v[216:219], v[4:7]
	v_mfma_f32_16x16x32_bf16 v[0:3], v[184:187], v[216:219], v[0:3]
	v_mfma_f32_16x16x32_bf16 v[52:55], v[170:173], v[196:199], v[52:55]
	v_mfma_f32_16x16x32_bf16 v[48:51], v[188:191], v[196:199], v[48:51]
	v_mfma_f32_16x16x32_bf16 v[36:39], v[170:173], v[204:207], v[36:39]
	v_mfma_f32_16x16x32_bf16 v[32:35], v[188:191], v[204:207], v[32:35]
	v_mfma_f32_16x16x32_bf16 v[20:23], v[170:173], v[212:215], v[20:23]
	v_mfma_f32_16x16x32_bf16 v[16:19], v[188:191], v[212:215], v[16:19]
	v_mfma_f32_16x16x32_bf16 v[4:7], v[170:173], v[220:223], v[4:7]
	v_mfma_f32_16x16x32_bf16 v[0:3], v[188:191], v[220:223], v[0:3]
	s_setprio 0
	s_barrier
	s_add_i32 s33, 0, 0x18000
	v_add_u32_e32 v138, s33, v150
	s_add_i32 s43, 0, 0x1c000
	ds_read_b128 v[146:149], v138
	ds_read_b128 v[154:157], v138 offset:1024
	ds_read_b128 v[158:161], v138 offset:2048
	ds_read_b128 v[162:165], v138 offset:3072
	v_add_u32_e32 v138, s43, v150
	ds_read_b128 v[166:169], v138
	ds_read_b128 v[170:173], v138 offset:1024
	ds_read_b128 v[184:187], v138 offset:2048
	ds_read_b128 v[188:191], v138 offset:3072
	s_add_u32 s50, s50, 0x20000
	s_addc_u32 s51, s51, 0
	s_mov_b32 m0, s55
	v_lshl_add_u64 v[228:229], s[50:51], 0, v[136:137]
	ds_read_b128 v[192:195], v152 offset:32768
	ds_read_b128 v[196:199], v152 offset:33792
	ds_read_b128 v[200:203], v152 offset:34816
	ds_read_b128 v[204:207], v152 offset:35840
	ds_read_b128 v[208:211], v152 offset:36864
	ds_read_b128 v[212:215], v152 offset:37888
	ds_read_b128 v[216:219], v152 offset:38912
	ds_read_b128 v[220:223], v152 offset:39936
	global_load_lds_dwordx4 v[228:229], off
	v_lshl_add_u64 v[228:229], s[50:51], 0, v[132:133]
	s_mov_b32 m0, s56
	s_nop 0
	global_load_lds_dwordx4 v[228:229], off
	s_waitcnt vmcnt(8)
	s_waitcnt lgkmcnt(0)
	s_barrier
	s_setprio 1
	s_waitcnt lgkmcnt(0)
	v_mfma_f32_16x16x32_bf16 v[126:129], v[146:149], v[192:195], v[126:129]
	v_mfma_f32_16x16x32_bf16 v[122:125], v[158:161], v[192:195], v[122:125]
	v_mfma_f32_16x16x32_bf16 v[110:113], v[146:149], v[200:203], v[110:113]
	v_mfma_f32_16x16x32_bf16 v[106:109], v[158:161], v[200:203], v[106:109]
	v_mfma_f32_16x16x32_bf16 v[94:97], v[146:149], v[208:211], v[94:97]
	v_mfma_f32_16x16x32_bf16 v[90:93], v[158:161], v[208:211], v[90:93]
	v_mfma_f32_16x16x32_bf16 v[78:81], v[146:149], v[216:219], v[78:81]
	v_mfma_f32_16x16x32_bf16 v[74:77], v[158:161], v[216:219], v[74:77]
	v_mfma_f32_16x16x32_bf16 v[126:129], v[154:157], v[196:199], v[126:129]
	v_mfma_f32_16x16x32_bf16 v[122:125], v[162:165], v[196:199], v[122:125]
	v_mfma_f32_16x16x32_bf16 v[110:113], v[154:157], v[204:207], v[110:113]
	v_mfma_f32_16x16x32_bf16 v[106:109], v[162:165], v[204:207], v[106:109]
	v_mfma_f32_16x16x32_bf16 v[94:97], v[154:157], v[212:215], v[94:97]
	v_mfma_f32_16x16x32_bf16 v[90:93], v[162:165], v[212:215], v[90:93]
	v_mfma_f32_16x16x32_bf16 v[78:81], v[154:157], v[220:223], v[78:81]
	v_mfma_f32_16x16x32_bf16 v[74:77], v[162:165], v[220:223], v[74:77]
	v_mfma_f32_16x16x32_bf16 v[118:121], v[166:169], v[192:195], v[118:121]
	v_mfma_f32_16x16x32_bf16 v[114:117], v[184:187], v[192:195], v[114:117]
	v_mfma_f32_16x16x32_bf16 v[102:105], v[166:169], v[200:203], v[102:105]
	v_mfma_f32_16x16x32_bf16 v[98:101], v[184:187], v[200:203], v[98:101]
	v_mfma_f32_16x16x32_bf16 v[86:89], v[166:169], v[208:211], v[86:89]
	v_mfma_f32_16x16x32_bf16 v[82:85], v[184:187], v[208:211], v[82:85]
	v_mfma_f32_16x16x32_bf16 v[70:73], v[166:169], v[216:219], v[70:73]
	v_mfma_f32_16x16x32_bf16 v[66:69], v[184:187], v[216:219], v[66:69]
	v_mfma_f32_16x16x32_bf16 v[118:121], v[170:173], v[196:199], v[118:121]
	v_mfma_f32_16x16x32_bf16 v[114:117], v[188:191], v[196:199], v[114:117]
	v_mfma_f32_16x16x32_bf16 v[102:105], v[170:173], v[204:207], v[102:105]
	v_mfma_f32_16x16x32_bf16 v[98:101], v[188:191], v[204:207], v[98:101]
	v_mfma_f32_16x16x32_bf16 v[86:89], v[170:173], v[212:215], v[86:89]
	v_mfma_f32_16x16x32_bf16 v[82:85], v[188:191], v[212:215], v[82:85]
	v_mfma_f32_16x16x32_bf16 v[70:73], v[170:173], v[220:223], v[70:73]
	v_mfma_f32_16x16x32_bf16 v[66:69], v[188:191], v[220:223], v[66:69]
	s_setprio 0
	s_barrier
	s_add_i32 s33, s33, s52
	v_lshl_add_u64 v[174:175], v[174:175], 0, s[14:15]
	s_mov_b32 m0, s33
	ds_read_b128 v[192:195], v152 offset:49152
	ds_read_b128 v[196:199], v152 offset:50176
	ds_read_b128 v[200:203], v152 offset:51200
	ds_read_b128 v[204:207], v152 offset:52224
	ds_read_b128 v[208:211], v152 offset:53248
	ds_read_b128 v[212:215], v152 offset:54272
	ds_read_b128 v[216:219], v152 offset:55296
	ds_read_b128 v[220:223], v152 offset:56320
	global_load_lds_dwordx4 v[174:175], off
	s_add_i32 m0, s33, 0x2000
	s_add_u32 s4, s4, 0x20080
	v_lshl_add_u64 v[174:175], v[182:183], 0, s[14:15]
	s_addc_u32 s5, s5, 0
	s_add_i32 s33, s43, s52
	global_load_lds_dwordx4 v[174:175], off
	v_lshl_add_u64 v[174:175], s[4:5], 0, v[134:135]
	s_mov_b32 m0, s33
	s_nop 0
	global_load_lds_dwordx4 v[174:175], off
	v_lshl_add_u64 v[174:175], s[4:5], 0, v[130:131]
	s_add_i32 m0, s33, 0x2000
	s_nop 0
	global_load_lds_dwordx4 v[174:175], off
	v_lshl_add_u64 v[174:175], v[224:225], 0, s[14:15]
	s_mov_b32 m0, s28
	s_nop 0
	global_load_lds_dwordx4 v[174:175], off
	v_lshl_add_u64 v[174:175], v[226:227], 0, s[14:15]
	s_mov_b32 m0, s57
	s_nop 0
	global_load_lds_dwordx4 v[174:175], off
	s_waitcnt vmcnt(8)
	s_waitcnt lgkmcnt(0)
	s_barrier
	s_setprio 1
	s_waitcnt lgkmcnt(0)
	v_mfma_f32_16x16x32_bf16 v[60:63], v[146:149], v[192:195], v[60:63]
	v_mfma_f32_16x16x32_bf16 v[56:59], v[158:161], v[192:195], v[56:59]
	v_mfma_f32_16x16x32_bf16 v[44:47], v[146:149], v[200:203], v[44:47]
	v_mfma_f32_16x16x32_bf16 v[40:43], v[158:161], v[200:203], v[40:43]
	v_mfma_f32_16x16x32_bf16 v[28:31], v[146:149], v[208:211], v[28:31]
	v_mfma_f32_16x16x32_bf16 v[24:27], v[158:161], v[208:211], v[24:27]
	v_mfma_f32_16x16x32_bf16 v[12:15], v[146:149], v[216:219], v[12:15]
	v_mfma_f32_16x16x32_bf16 v[8:11], v[158:161], v[216:219], v[8:11]
	v_mfma_f32_16x16x32_bf16 v[60:63], v[154:157], v[196:199], v[60:63]
	v_mfma_f32_16x16x32_bf16 v[56:59], v[162:165], v[196:199], v[56:59]
	v_mfma_f32_16x16x32_bf16 v[44:47], v[154:157], v[204:207], v[44:47]
	v_mfma_f32_16x16x32_bf16 v[40:43], v[162:165], v[204:207], v[40:43]
	v_mfma_f32_16x16x32_bf16 v[28:31], v[154:157], v[212:215], v[28:31]
	v_mfma_f32_16x16x32_bf16 v[24:27], v[162:165], v[212:215], v[24:27]
	v_mfma_f32_16x16x32_bf16 v[12:15], v[154:157], v[220:223], v[12:15]
	v_mfma_f32_16x16x32_bf16 v[8:11], v[162:165], v[220:223], v[8:11]
	v_mfma_f32_16x16x32_bf16 v[52:55], v[166:169], v[192:195], v[52:55]
	v_mfma_f32_16x16x32_bf16 v[48:51], v[184:187], v[192:195], v[48:51]
	v_mfma_f32_16x16x32_bf16 v[36:39], v[166:169], v[200:203], v[36:39]
	v_mfma_f32_16x16x32_bf16 v[32:35], v[184:187], v[200:203], v[32:35]
	v_mfma_f32_16x16x32_bf16 v[20:23], v[166:169], v[208:211], v[20:23]
	v_mfma_f32_16x16x32_bf16 v[16:19], v[184:187], v[208:211], v[16:19]
	v_mfma_f32_16x16x32_bf16 v[4:7], v[166:169], v[216:219], v[4:7]
	v_mfma_f32_16x16x32_bf16 v[0:3], v[184:187], v[216:219], v[0:3]
	v_mfma_f32_16x16x32_bf16 v[52:55], v[170:173], v[196:199], v[52:55]
	v_mfma_f32_16x16x32_bf16 v[48:51], v[188:191], v[196:199], v[48:51]
	v_mfma_f32_16x16x32_bf16 v[36:39], v[170:173], v[204:207], v[36:39]
	v_mfma_f32_16x16x32_bf16 v[32:35], v[188:191], v[204:207], v[32:35]
	v_mfma_f32_16x16x32_bf16 v[20:23], v[170:173], v[212:215], v[20:23]
	v_mfma_f32_16x16x32_bf16 v[16:19], v[188:191], v[212:215], v[16:19]
	v_mfma_f32_16x16x32_bf16 v[4:7], v[170:173], v[220:223], v[4:7]
	v_mfma_f32_16x16x32_bf16 v[0:3], v[188:191], v[220:223], v[0:3]
	s_setprio 0
	s_barrier
	s_add_i32 s29, s29, 2
	s_add_u32 s36, s36, 0x100
	s_addc_u32 s37, s37, 0
	s_add_u32 s24, s24, 0x100
	s_addc_u32 s25, s25, 0
	s_cmp_gt_u32 s29, 5
	s_cbranch_scc0 .LBB0_244
	s_and_b64 vcc, exec, s[40:41]
	s_cbranch_vccz .LBB0_247
	s_barrier

.LBB0_581:
	s_add_u32 s4, s0, 0xfffc0080
	s_addc_u32 s5, s1, -1
	s_add_i32 s24, 0, 0x10000
	s_cmp_eq_u32 s21, 12
	s_cselect_b32 s37, s8, s5
	s_cselect_b32 s36, s9, s4
	v_add_u32_e32 v138, s24, v191
	s_cselect_b32 s5, s10, s20
	s_cselect_b32 s4, s18, s19
	s_add_i32 s28, 0, 0x14000
	ds_read_b128 v[130:133], v138
	ds_read_b128 v[134:137], v138 offset:1024
	ds_read_b128 v[158:161], v138 offset:2048
	ds_read_b128 v[162:165], v138 offset:3072
	v_add_u32_e32 v138, s28, v191
	ds_read_b128 v[196:199], v138
	ds_read_b128 v[200:203], v138 offset:1024
	ds_read_b128 v[204:207], v138 offset:2048
	ds_read_b128 v[208:211], v138 offset:3072
	v_lshl_add_u64 v[166:167], s[0:1], 0, v[152:153]
	s_add_i32 m0, s61, 0xc000
	ds_read_b128 v[212:215], v194
	ds_read_b128 v[216:219], v194 offset:1024
	ds_read_b128 v[220:223], v194 offset:2048
	ds_read_b128 v[224:227], v194 offset:3072
	ds_read_b128 v[228:231], v194 offset:4096
	ds_read_b128 v[232:235], v194 offset:5120
	ds_read_b128 v[236:239], v194 offset:6144
	ds_read_b128 v[240:243], v194 offset:7168
	global_load_lds_dwordx4 v[166:167], off
	v_lshl_add_u64 v[166:167], s[0:1], 0, v[154:155]
	s_add_i32 m0, s61, 0xe000
	s_nop 0
	global_load_lds_dwordx4 v[166:167], off
	s_waitcnt vmcnt(8)
	s_waitcnt lgkmcnt(0)
	s_barrier
	s_setprio 1
	s_waitcnt lgkmcnt(0)
	v_mfma_f32_16x16x32_bf16 v[126:129], v[130:133], v[212:215], v[126:129]
	v_mfma_f32_16x16x32_bf16 v[122:125], v[158:161], v[212:215], v[122:125]
	v_mfma_f32_16x16x32_bf16 v[110:113], v[130:133], v[220:223], v[110:113]
	v_mfma_f32_16x16x32_bf16 v[106:109], v[158:161], v[220:223], v[106:109]
	v_mfma_f32_16x16x32_bf16 v[94:97], v[130:133], v[228:231], v[94:97]
	v_mfma_f32_16x16x32_bf16 v[90:93], v[158:161], v[228:231], v[90:93]
	v_mfma_f32_16x16x32_bf16 v[78:81], v[130:133], v[236:239], v[78:81]
	v_mfma_f32_16x16x32_bf16 v[74:77], v[158:161], v[236:239], v[74:77]
	v_mfma_f32_16x16x32_bf16 v[126:129], v[134:137], v[216:219], v[126:129]
	v_mfma_f32_16x16x32_bf16 v[122:125], v[162:165], v[216:219], v[122:125]
	v_mfma_f32_16x16x32_bf16 v[110:113], v[134:137], v[224:227], v[110:113]
	v_mfma_f32_16x16x32_bf16 v[106:109], v[162:165], v[224:227], v[106:109]
	v_mfma_f32_16x16x32_bf16 v[94:97], v[134:137], v[232:235], v[94:97]
	v_mfma_f32_16x16x32_bf16 v[90:93], v[162:165], v[232:235], v[90:93]
	v_mfma_f32_16x16x32_bf16 v[78:81], v[134:137], v[240:243], v[78:81]
	v_mfma_f32_16x16x32_bf16 v[74:77], v[162:165], v[240:243], v[74:77]
	v_mfma_f32_16x16x32_bf16 v[118:121], v[196:199], v[212:215], v[118:121]
	v_mfma_f32_16x16x32_bf16 v[114:117], v[204:207], v[212:215], v[114:117]
	v_mfma_f32_16x16x32_bf16 v[102:105], v[196:199], v[220:223], v[102:105]
	v_mfma_f32_16x16x32_bf16 v[98:101], v[204:207], v[220:223], v[98:101]
	v_mfma_f32_16x16x32_bf16 v[86:89], v[196:199], v[228:231], v[86:89]
	v_mfma_f32_16x16x32_bf16 v[82:85], v[204:207], v[228:231], v[82:85]
	v_mfma_f32_16x16x32_bf16 v[70:73], v[196:199], v[236:239], v[70:73]
	v_mfma_f32_16x16x32_bf16 v[66:69], v[204:207], v[236:239], v[66:69]
	v_mfma_f32_16x16x32_bf16 v[118:121], v[200:203], v[216:219], v[118:121]
	v_mfma_f32_16x16x32_bf16 v[114:117], v[208:211], v[216:219], v[114:117]
	v_mfma_f32_16x16x32_bf16 v[102:105], v[200:203], v[224:227], v[102:105]
	v_mfma_f32_16x16x32_bf16 v[98:101], v[208:211], v[224:227], v[98:101]
	v_mfma_f32_16x16x32_bf16 v[86:89], v[200:203], v[232:235], v[86:89]
	v_mfma_f32_16x16x32_bf16 v[82:85], v[208:211], v[232:235], v[82:85]
	v_mfma_f32_16x16x32_bf16 v[70:73], v[200:203], v[240:243], v[70:73]
	v_mfma_f32_16x16x32_bf16 v[66:69], v[208:211], v[240:243], v[66:69]
	s_setprio 0
	s_barrier
	s_add_i32 s24, s24, s60
	v_lshl_add_u64 v[166:167], s[4:5], 0, v[146:147]
	s_mov_b32 m0, s24
	ds_read_b128 v[212:215], v194 offset:16384
	ds_read_b128 v[216:219], v194 offset:17408
	ds_read_b128 v[220:223], v194 offset:18432
	ds_read_b128 v[224:227], v194 offset:19456
	ds_read_b128 v[228:231], v194 offset:20480
	ds_read_b128 v[232:235], v194 offset:21504
	ds_read_b128 v[236:239], v194 offset:22528
	ds_read_b128 v[240:243], v194 offset:23552
	global_load_lds_dwordx4 v[166:167], off
	s_add_i32 m0, s24, 0x2000
	s_add_u32 s24, s4, 0x40000
	v_lshl_add_u64 v[244:245], s[4:5], 0, v[142:143]
	s_addc_u32 s25, s5, 0
	s_add_i32 s28, s28, s60
	global_load_lds_dwordx4 v[244:245], off
	v_lshl_add_u64 v[246:247], s[24:25], 0, v[146:147]
	s_mov_b32 m0, s28
	v_lshl_add_u64 v[248:249], s[36:37], 0, v[144:145]
	global_load_lds_dwordx4 v[246:247], off
	v_lshl_add_u64 v[246:247], s[24:25], 0, v[142:143]
	s_add_i32 m0, s28, 0x2000
	s_nop 0
	global_load_lds_dwordx4 v[246:247], off
	v_lshl_add_u64 v[246:247], s[36:37], 0, v[148:149]
	s_mov_b32 m0, s61
	s_nop 0
	global_load_lds_dwordx4 v[246:247], off
	s_mov_b32 m0, s62
	s_nop 0
	global_load_lds_dwordx4 v[248:249], off
	s_waitcnt vmcnt(8)
	s_waitcnt lgkmcnt(0)
	s_barrier
	s_setprio 1
	s_waitcnt lgkmcnt(0)
	v_mfma_f32_16x16x32_bf16 v[60:63], v[130:133], v[212:215], v[60:63]
	v_mfma_f32_16x16x32_bf16 v[56:59], v[158:161], v[212:215], v[56:59]
	v_mfma_f32_16x16x32_bf16 v[44:47], v[130:133], v[220:223], v[44:47]
	v_mfma_f32_16x16x32_bf16 v[40:43], v[158:161], v[220:223], v[40:43]
	v_mfma_f32_16x16x32_bf16 v[28:31], v[130:133], v[228:231], v[28:31]
	v_mfma_f32_16x16x32_bf16 v[24:27], v[158:161], v[228:231], v[24:27]
	v_mfma_f32_16x16x32_bf16 v[12:15], v[130:133], v[236:239], v[12:15]
	v_mfma_f32_16x16x32_bf16 v[8:11], v[158:161], v[236:239], v[8:11]
	v_mfma_f32_16x16x32_bf16 v[60:63], v[134:137], v[216:219], v[60:63]
	v_mfma_f32_16x16x32_bf16 v[56:59], v[162:165], v[216:219], v[56:59]
	v_mfma_f32_16x16x32_bf16 v[44:47], v[134:137], v[224:227], v[44:47]
	v_mfma_f32_16x16x32_bf16 v[40:43], v[162:165], v[224:227], v[40:43]
	v_mfma_f32_16x16x32_bf16 v[28:31], v[134:137], v[232:235], v[28:31]
	v_mfma_f32_16x16x32_bf16 v[24:27], v[162:165], v[232:235], v[24:27]
	v_mfma_f32_16x16x32_bf16 v[12:15], v[134:137], v[240:243], v[12:15]
	v_mfma_f32_16x16x32_bf16 v[8:11], v[162:165], v[240:243], v[8:11]
	v_mfma_f32_16x16x32_bf16 v[52:55], v[196:199], v[212:215], v[52:55]
	v_mfma_f32_16x16x32_bf16 v[48:51], v[204:207], v[212:215], v[48:51]
	v_mfma_f32_16x16x32_bf16 v[36:39], v[196:199], v[220:223], v[36:39]
	v_mfma_f32_16x16x32_bf16 v[32:35], v[204:207], v[220:223], v[32:35]
	v_mfma_f32_16x16x32_bf16 v[20:23], v[196:199], v[228:231], v[20:23]
	v_mfma_f32_16x16x32_bf16 v[16:19], v[204:207], v[228:231], v[16:19]
	v_mfma_f32_16x16x32_bf16 v[4:7], v[196:199], v[236:239], v[4:7]
	v_mfma_f32_16x16x32_bf16 v[0:3], v[204:207], v[236:239], v[0:3]
	v_mfma_f32_16x16x32_bf16 v[52:55], v[200:203], v[216:219], v[52:55]
	v_mfma_f32_16x16x32_bf16 v[48:51], v[208:211], v[216:219], v[48:51]
	v_mfma_f32_16x16x32_bf16 v[36:39], v[200:203], v[224:227], v[36:39]
	v_mfma_f32_16x16x32_bf16 v[32:35], v[208:211], v[224:227], v[32:35]
	v_mfma_f32_16x16x32_bf16 v[20:23], v[200:203], v[232:235], v[20:23]
	v_mfma_f32_16x16x32_bf16 v[16:19], v[208:211], v[232:235], v[16:19]
	v_mfma_f32_16x16x32_bf16 v[4:7], v[200:203], v[240:243], v[4:7]
	v_mfma_f32_16x16x32_bf16 v[0:3], v[208:211], v[240:243], v[0:3]
	s_setprio 0
	s_barrier
	s_add_i32 s28, 0, 0x18000
	v_add_u32_e32 v138, s28, v191
	s_add_i32 s29, 0, 0x1c000
	ds_read_b128 v[130:133], v138
	ds_read_b128 v[134:137], v138 offset:1024
	ds_read_b128 v[158:161], v138 offset:2048
	ds_read_b128 v[162:165], v138 offset:3072
	v_add_u32_e32 v138, s29, v191
	ds_read_b128 v[196:199], v138
	ds_read_b128 v[200:203], v138 offset:1024
	ds_read_b128 v[204:207], v138 offset:2048
	ds_read_b128 v[208:211], v138 offset:3072
	s_add_u32 s24, s36, 0x40000
	s_addc_u32 s25, s37, 0
	s_mov_b32 m0, s63
	v_lshl_add_u64 v[182:183], s[24:25], 0, v[148:149]
	ds_read_b128 v[212:215], v194 offset:32768
	ds_read_b128 v[216:219], v194 offset:33792
	ds_read_b128 v[220:223], v194 offset:34816
	ds_read_b128 v[224:227], v194 offset:35840
	ds_read_b128 v[228:231], v194 offset:36864
	ds_read_b128 v[232:235], v194 offset:37888
	ds_read_b128 v[236:239], v194 offset:38912
	ds_read_b128 v[240:243], v194 offset:39936
	global_load_lds_dwordx4 v[182:183], off
	v_lshl_add_u64 v[182:183], s[24:25], 0, v[144:145]
	s_mov_b32 m0, s64
	s_nop 0
	global_load_lds_dwordx4 v[182:183], off
	s_waitcnt vmcnt(8)
	s_waitcnt lgkmcnt(0)
	s_barrier
	s_setprio 1
	s_waitcnt lgkmcnt(0)
	v_mfma_f32_16x16x32_bf16 v[126:129], v[130:133], v[212:215], v[126:129]
	v_mfma_f32_16x16x32_bf16 v[122:125], v[158:161], v[212:215], v[122:125]
	v_mfma_f32_16x16x32_bf16 v[110:113], v[130:133], v[220:223], v[110:113]
	v_mfma_f32_16x16x32_bf16 v[106:109], v[158:161], v[220:223], v[106:109]
	v_mfma_f32_16x16x32_bf16 v[94:97], v[130:133], v[228:231], v[94:97]
	v_mfma_f32_16x16x32_bf16 v[90:93], v[158:161], v[228:231], v[90:93]
	v_mfma_f32_16x16x32_bf16 v[78:81], v[130:133], v[236:239], v[78:81]
	v_mfma_f32_16x16x32_bf16 v[74:77], v[158:161], v[236:239], v[74:77]
	v_mfma_f32_16x16x32_bf16 v[126:129], v[134:137], v[216:219], v[126:129]
	v_mfma_f32_16x16x32_bf16 v[122:125], v[162:165], v[216:219], v[122:125]
	v_mfma_f32_16x16x32_bf16 v[110:113], v[134:137], v[224:227], v[110:113]
	v_mfma_f32_16x16x32_bf16 v[106:109], v[162:165], v[224:227], v[106:109]
	v_mfma_f32_16x16x32_bf16 v[94:97], v[134:137], v[232:235], v[94:97]
	v_mfma_f32_16x16x32_bf16 v[90:93], v[162:165], v[232:235], v[90:93]
	v_mfma_f32_16x16x32_bf16 v[78:81], v[134:137], v[240:243], v[78:81]
	v_mfma_f32_16x16x32_bf16 v[74:77], v[162:165], v[240:243], v[74:77]
	v_mfma_f32_16x16x32_bf16 v[118:121], v[196:199], v[212:215], v[118:121]
	v_mfma_f32_16x16x32_bf16 v[114:117], v[204:207], v[212:215], v[114:117]
	v_mfma_f32_16x16x32_bf16 v[102:105], v[196:199], v[220:223], v[102:105]
	v_mfma_f32_16x16x32_bf16 v[98:101], v[204:207], v[220:223], v[98:101]
	v_mfma_f32_16x16x32_bf16 v[86:89], v[196:199], v[228:231], v[86:89]
	v_mfma_f32_16x16x32_bf16 v[82:85], v[204:207], v[228:231], v[82:85]
	v_mfma_f32_16x16x32_bf16 v[70:73], v[196:199], v[236:239], v[70:73]
	v_mfma_f32_16x16x32_bf16 v[66:69], v[204:207], v[236:239], v[66:69]
	v_mfma_f32_16x16x32_bf16 v[118:121], v[200:203], v[216:219], v[118:121]
	v_mfma_f32_16x16x32_bf16 v[114:117], v[208:211], v[216:219], v[114:117]
	v_mfma_f32_16x16x32_bf16 v[102:105], v[200:203], v[224:227], v[102:105]
	v_mfma_f32_16x16x32_bf16 v[98:101], v[208:211], v[224:227], v[98:101]
	v_mfma_f32_16x16x32_bf16 v[86:89], v[200:203], v[232:235], v[86:89]
	v_mfma_f32_16x16x32_bf16 v[82:85], v[208:211], v[232:235], v[82:85]
	v_mfma_f32_16x16x32_bf16 v[70:73], v[200:203], v[240:243], v[70:73]
	v_mfma_f32_16x16x32_bf16 v[66:69], v[208:211], v[240:243], v[66:69]
	s_setprio 0
	s_barrier
	s_add_i32 s24, s28, s60
	v_lshl_add_u64 v[166:167], v[166:167], 0, s[14:15]
	s_mov_b32 m0, s24
	ds_read_b128 v[212:215], v194 offset:49152
	ds_read_b128 v[216:219], v194 offset:50176
	ds_read_b128 v[220:223], v194 offset:51200
	ds_read_b128 v[224:227], v194 offset:52224
	ds_read_b128 v[228:231], v194 offset:53248
	ds_read_b128 v[232:235], v194 offset:54272
	ds_read_b128 v[236:239], v194 offset:55296
	ds_read_b128 v[240:243], v194 offset:56320
	global_load_lds_dwordx4 v[166:167], off
	s_add_i32 m0, s24, 0x2000
	s_add_u32 s4, s4, 0x40080
	v_lshl_add_u64 v[166:167], v[244:245], 0, s[14:15]
	s_addc_u32 s5, s5, 0
	s_add_i32 s24, s29, s60
	global_load_lds_dwordx4 v[166:167], off
	v_lshl_add_u64 v[166:167], s[4:5], 0, v[146:147]
	s_mov_b32 m0, s24
	s_nop 0
	global_load_lds_dwordx4 v[166:167], off
	v_lshl_add_u64 v[166:167], s[4:5], 0, v[142:143]
	s_add_i32 m0, s24, 0x2000
	s_nop 0
	global_load_lds_dwordx4 v[166:167], off
	v_lshl_add_u64 v[166:167], v[246:247], 0, s[14:15]
	s_mov_b32 m0, s65
	s_nop 0
	global_load_lds_dwordx4 v[166:167], off
	v_lshl_add_u64 v[166:167], v[248:249], 0, s[14:15]
	s_mov_b32 m0, s70
	s_nop 0
	global_load_lds_dwordx4 v[166:167], off
	s_waitcnt vmcnt(8)
	s_waitcnt lgkmcnt(0)
	s_barrier
	s_setprio 1
	s_waitcnt lgkmcnt(0)
	v_mfma_f32_16x16x32_bf16 v[60:63], v[130:133], v[212:215], v[60:63]
	v_mfma_f32_16x16x32_bf16 v[56:59], v[158:161], v[212:215], v[56:59]
	v_mfma_f32_16x16x32_bf16 v[44:47], v[130:133], v[220:223], v[44:47]
	v_mfma_f32_16x16x32_bf16 v[40:43], v[158:161], v[220:223], v[40:43]
	v_mfma_f32_16x16x32_bf16 v[28:31], v[130:133], v[228:231], v[28:31]
	v_mfma_f32_16x16x32_bf16 v[24:27], v[158:161], v[228:231], v[24:27]
	v_mfma_f32_16x16x32_bf16 v[12:15], v[130:133], v[236:239], v[12:15]
	v_mfma_f32_16x16x32_bf16 v[8:11], v[158:161], v[236:239], v[8:11]
	v_mfma_f32_16x16x32_bf16 v[60:63], v[134:137], v[216:219], v[60:63]
	v_mfma_f32_16x16x32_bf16 v[56:59], v[162:165], v[216:219], v[56:59]
	v_mfma_f32_16x16x32_bf16 v[44:47], v[134:137], v[224:227], v[44:47]
	v_mfma_f32_16x16x32_bf16 v[40:43], v[162:165], v[224:227], v[40:43]
	v_mfma_f32_16x16x32_bf16 v[28:31], v[134:137], v[232:235], v[28:31]
	v_mfma_f32_16x16x32_bf16 v[24:27], v[162:165], v[232:235], v[24:27]
	v_mfma_f32_16x16x32_bf16 v[12:15], v[134:137], v[240:243], v[12:15]
	v_mfma_f32_16x16x32_bf16 v[8:11], v[162:165], v[240:243], v[8:11]
	v_mfma_f32_16x16x32_bf16 v[52:55], v[196:199], v[212:215], v[52:55]
	v_mfma_f32_16x16x32_bf16 v[48:51], v[204:207], v[212:215], v[48:51]
	v_mfma_f32_16x16x32_bf16 v[36:39], v[196:199], v[220:223], v[36:39]
	v_mfma_f32_16x16x32_bf16 v[32:35], v[204:207], v[220:223], v[32:35]
	v_mfma_f32_16x16x32_bf16 v[20:23], v[196:199], v[228:231], v[20:23]
	v_mfma_f32_16x16x32_bf16 v[16:19], v[204:207], v[228:231], v[16:19]
	v_mfma_f32_16x16x32_bf16 v[4:7], v[196:199], v[236:239], v[4:7]
	v_mfma_f32_16x16x32_bf16 v[0:3], v[204:207], v[236:239], v[0:3]
	v_mfma_f32_16x16x32_bf16 v[52:55], v[200:203], v[216:219], v[52:55]
	v_mfma_f32_16x16x32_bf16 v[48:51], v[208:211], v[216:219], v[48:51]
	v_mfma_f32_16x16x32_bf16 v[36:39], v[200:203], v[224:227], v[36:39]
	v_mfma_f32_16x16x32_bf16 v[32:35], v[208:211], v[224:227], v[32:35]
	v_mfma_f32_16x16x32_bf16 v[20:23], v[200:203], v[232:235], v[20:23]
	v_mfma_f32_16x16x32_bf16 v[16:19], v[208:211], v[232:235], v[16:19]
	v_mfma_f32_16x16x32_bf16 v[4:7], v[200:203], v[240:243], v[4:7]
	v_mfma_f32_16x16x32_bf16 v[0:3], v[208:211], v[240:243], v[0:3]
	s_setprio 0
	s_barrier
	s_add_i32 s21, s21, 2
	s_add_u32 s0, s0, 0x100
	s_addc_u32 s1, s1, 0
	s_add_u32 s19, s19, 0x100
	s_addc_u32 s20, s20, 0
	s_cmp_gt_u32 s21, 13
	s_cbranch_scc0 .LBB0_581
	s_and_b64 vcc, exec, s[40:41]
	s_cbranch_vccz .LBB0_584
	s_barrier

.LBB0_929:
	s_add_u32 s4, s42, 0xfffc0080
	s_addc_u32 s5, s43, -1
	s_add_i32 s54, 0, 0x10000
	s_cmp_eq_u32 s49, 12
	s_cselect_b32 s53, s28, s5
	s_cselect_b32 s52, s29, s4
	v_add_u32_e32 v138, s54, v158
	s_cselect_b32 s5, s33, s45
	s_cselect_b32 s4, s39, s41
	s_add_i32 s56, 0, 0x14000
	ds_read_b128 v[142:145], v138
	ds_read_b128 v[146:149], v138 offset:1024
	ds_read_b128 v[150:153], v138 offset:2048
	ds_read_b128 v[154:157], v138 offset:3072
	v_add_u32_e32 v138, s56, v158
	ds_read_b128 v[162:165], v138
	ds_read_b128 v[166:169], v138 offset:1024
	ds_read_b128 v[170:173], v138 offset:2048
	ds_read_b128 v[184:187], v138 offset:3072
	v_lshl_add_u64 v[174:175], s[42:43], 0, v[134:135]
	s_add_i32 m0, s3, 0xc000
	ds_read_b128 v[188:191], v160
	ds_read_b128 v[192:195], v160 offset:1024
	ds_read_b128 v[196:199], v160 offset:2048
	ds_read_b128 v[200:203], v160 offset:3072
	ds_read_b128 v[204:207], v160 offset:4096
	ds_read_b128 v[208:211], v160 offset:5120
	ds_read_b128 v[212:215], v160 offset:6144
	ds_read_b128 v[216:219], v160 offset:7168
	global_load_lds_dwordx4 v[174:175], off
	v_lshl_add_u64 v[174:175], s[42:43], 0, v[136:137]
	s_add_i32 m0, s3, 0xe000
	s_nop 0
	global_load_lds_dwordx4 v[174:175], off
	s_waitcnt vmcnt(8)
	s_waitcnt lgkmcnt(0)
	s_barrier
	s_setprio 1
	s_waitcnt lgkmcnt(0)
	v_mfma_f32_16x16x32_bf16 v[126:129], v[142:145], v[188:191], v[126:129]
	v_mfma_f32_16x16x32_bf16 v[122:125], v[150:153], v[188:191], v[122:125]
	v_mfma_f32_16x16x32_bf16 v[110:113], v[142:145], v[196:199], v[110:113]
	v_mfma_f32_16x16x32_bf16 v[106:109], v[150:153], v[196:199], v[106:109]
	v_mfma_f32_16x16x32_bf16 v[94:97], v[142:145], v[204:207], v[94:97]
	v_mfma_f32_16x16x32_bf16 v[90:93], v[150:153], v[204:207], v[90:93]
	v_mfma_f32_16x16x32_bf16 v[78:81], v[142:145], v[212:215], v[78:81]
	v_mfma_f32_16x16x32_bf16 v[74:77], v[150:153], v[212:215], v[74:77]
	v_mfma_f32_16x16x32_bf16 v[126:129], v[146:149], v[192:195], v[126:129]
	v_mfma_f32_16x16x32_bf16 v[122:125], v[154:157], v[192:195], v[122:125]
	v_mfma_f32_16x16x32_bf16 v[110:113], v[146:149], v[200:203], v[110:113]
	v_mfma_f32_16x16x32_bf16 v[106:109], v[154:157], v[200:203], v[106:109]
	v_mfma_f32_16x16x32_bf16 v[94:97], v[146:149], v[208:211], v[94:97]
	v_mfma_f32_16x16x32_bf16 v[90:93], v[154:157], v[208:211], v[90:93]
	v_mfma_f32_16x16x32_bf16 v[78:81], v[146:149], v[216:219], v[78:81]
	v_mfma_f32_16x16x32_bf16 v[74:77], v[154:157], v[216:219], v[74:77]
	v_mfma_f32_16x16x32_bf16 v[118:121], v[162:165], v[188:191], v[118:121]
	v_mfma_f32_16x16x32_bf16 v[114:117], v[170:173], v[188:191], v[114:117]
	v_mfma_f32_16x16x32_bf16 v[102:105], v[162:165], v[196:199], v[102:105]
	v_mfma_f32_16x16x32_bf16 v[98:101], v[170:173], v[196:199], v[98:101]
	v_mfma_f32_16x16x32_bf16 v[86:89], v[162:165], v[204:207], v[86:89]
	v_mfma_f32_16x16x32_bf16 v[82:85], v[170:173], v[204:207], v[82:85]
	v_mfma_f32_16x16x32_bf16 v[70:73], v[162:165], v[212:215], v[70:73]
	v_mfma_f32_16x16x32_bf16 v[66:69], v[170:173], v[212:215], v[66:69]
	v_mfma_f32_16x16x32_bf16 v[118:121], v[166:169], v[192:195], v[118:121]
	v_mfma_f32_16x16x32_bf16 v[114:117], v[184:187], v[192:195], v[114:117]
	v_mfma_f32_16x16x32_bf16 v[102:105], v[166:169], v[200:203], v[102:105]
	v_mfma_f32_16x16x32_bf16 v[98:101], v[184:187], v[200:203], v[98:101]
	v_mfma_f32_16x16x32_bf16 v[86:89], v[166:169], v[208:211], v[86:89]
	v_mfma_f32_16x16x32_bf16 v[82:85], v[184:187], v[208:211], v[82:85]
	v_mfma_f32_16x16x32_bf16 v[70:73], v[166:169], v[216:219], v[70:73]
	v_mfma_f32_16x16x32_bf16 v[66:69], v[184:187], v[216:219], v[66:69]
	s_setprio 0
	s_barrier
	s_add_i32 s54, s54, s2
	v_lshl_add_u64 v[174:175], s[4:5], 0, v[130:131]
	s_mov_b32 m0, s54
	ds_read_b128 v[188:191], v160 offset:16384
	ds_read_b128 v[192:195], v160 offset:17408
	ds_read_b128 v[196:199], v160 offset:18432
	ds_read_b128 v[200:203], v160 offset:19456
	ds_read_b128 v[204:207], v160 offset:20480
	ds_read_b128 v[208:211], v160 offset:21504
	ds_read_b128 v[212:215], v160 offset:22528
	ds_read_b128 v[216:219], v160 offset:23552
	global_load_lds_dwordx4 v[174:175], off
	s_add_i32 m0, s54, 0x2000
	s_add_u32 s54, s4, 0x40000
	v_lshl_add_u64 v[182:183], s[4:5], 0, v[132:133]
	s_addc_u32 s55, s5, 0
	s_add_i32 s56, s56, s2
	global_load_lds_dwordx4 v[182:183], off
	v_lshl_add_u64 v[220:221], s[54:55], 0, v[130:131]
	s_mov_b32 m0, s56
	v_lshl_add_u64 v[222:223], s[52:53], 0, v[132:133]
	global_load_lds_dwordx4 v[220:221], off
	v_lshl_add_u64 v[220:221], s[54:55], 0, v[132:133]
	s_add_i32 m0, s56, 0x2000
	s_nop 0
	global_load_lds_dwordx4 v[220:221], off
	v_lshl_add_u64 v[220:221], s[52:53], 0, v[130:131]
	s_mov_b32 m0, s3
	s_nop 0
	global_load_lds_dwordx4 v[220:221], off
	s_mov_b32 m0, s10
	s_nop 0
	global_load_lds_dwordx4 v[222:223], off
	s_waitcnt vmcnt(8)
	s_waitcnt lgkmcnt(0)
	s_barrier
	s_setprio 1
	s_waitcnt lgkmcnt(0)
	v_mfma_f32_16x16x32_bf16 v[60:63], v[142:145], v[188:191], v[60:63]
	v_mfma_f32_16x16x32_bf16 v[56:59], v[150:153], v[188:191], v[56:59]
	v_mfma_f32_16x16x32_bf16 v[44:47], v[142:145], v[196:199], v[44:47]
	v_mfma_f32_16x16x32_bf16 v[40:43], v[150:153], v[196:199], v[40:43]
	v_mfma_f32_16x16x32_bf16 v[28:31], v[142:145], v[204:207], v[28:31]
	v_mfma_f32_16x16x32_bf16 v[24:27], v[150:153], v[204:207], v[24:27]
	v_mfma_f32_16x16x32_bf16 v[12:15], v[142:145], v[212:215], v[12:15]
	v_mfma_f32_16x16x32_bf16 v[8:11], v[150:153], v[212:215], v[8:11]
	v_mfma_f32_16x16x32_bf16 v[60:63], v[146:149], v[192:195], v[60:63]
	v_mfma_f32_16x16x32_bf16 v[56:59], v[154:157], v[192:195], v[56:59]
	v_mfma_f32_16x16x32_bf16 v[44:47], v[146:149], v[200:203], v[44:47]
	v_mfma_f32_16x16x32_bf16 v[40:43], v[154:157], v[200:203], v[40:43]
	v_mfma_f32_16x16x32_bf16 v[28:31], v[146:149], v[208:211], v[28:31]
	v_mfma_f32_16x16x32_bf16 v[24:27], v[154:157], v[208:211], v[24:27]
	v_mfma_f32_16x16x32_bf16 v[12:15], v[146:149], v[216:219], v[12:15]
	v_mfma_f32_16x16x32_bf16 v[8:11], v[154:157], v[216:219], v[8:11]
	v_mfma_f32_16x16x32_bf16 v[52:55], v[162:165], v[188:191], v[52:55]
	v_mfma_f32_16x16x32_bf16 v[48:51], v[170:173], v[188:191], v[48:51]
	v_mfma_f32_16x16x32_bf16 v[36:39], v[162:165], v[196:199], v[36:39]
	v_mfma_f32_16x16x32_bf16 v[32:35], v[170:173], v[196:199], v[32:35]
	v_mfma_f32_16x16x32_bf16 v[20:23], v[162:165], v[204:207], v[20:23]
	v_mfma_f32_16x16x32_bf16 v[16:19], v[170:173], v[204:207], v[16:19]
	v_mfma_f32_16x16x32_bf16 v[4:7], v[162:165], v[212:215], v[4:7]
	v_mfma_f32_16x16x32_bf16 v[0:3], v[170:173], v[212:215], v[0:3]
	v_mfma_f32_16x16x32_bf16 v[52:55], v[166:169], v[192:195], v[52:55]
	v_mfma_f32_16x16x32_bf16 v[48:51], v[184:187], v[192:195], v[48:51]
	v_mfma_f32_16x16x32_bf16 v[36:39], v[166:169], v[200:203], v[36:39]
	v_mfma_f32_16x16x32_bf16 v[32:35], v[184:187], v[200:203], v[32:35]
	v_mfma_f32_16x16x32_bf16 v[20:23], v[166:169], v[208:211], v[20:23]
	v_mfma_f32_16x16x32_bf16 v[16:19], v[184:187], v[208:211], v[16:19]
	v_mfma_f32_16x16x32_bf16 v[4:7], v[166:169], v[216:219], v[4:7]
	v_mfma_f32_16x16x32_bf16 v[0:3], v[184:187], v[216:219], v[0:3]
	s_setprio 0
	s_barrier
	s_add_i32 s54, 0, 0x18000
	v_add_u32_e32 v138, s54, v158
	s_add_i32 s55, 0, 0x1c000
	ds_read_b128 v[142:145], v138
	ds_read_b128 v[146:149], v138 offset:1024
	ds_read_b128 v[150:153], v138 offset:2048
	ds_read_b128 v[154:157], v138 offset:3072
	v_add_u32_e32 v138, s55, v158
	ds_read_b128 v[162:165], v138
	ds_read_b128 v[166:169], v138 offset:1024
	ds_read_b128 v[170:173], v138 offset:2048
	ds_read_b128 v[184:187], v138 offset:3072
	s_add_u32 s52, s52, 0x40000
	s_addc_u32 s53, s53, 0
	s_mov_b32 m0, s18
	v_lshl_add_u64 v[224:225], s[52:53], 0, v[130:131]
	ds_read_b128 v[188:191], v160 offset:32768
	ds_read_b128 v[192:195], v160 offset:33792
	ds_read_b128 v[196:199], v160 offset:34816
	ds_read_b128 v[200:203], v160 offset:35840
	ds_read_b128 v[204:207], v160 offset:36864
	ds_read_b128 v[208:211], v160 offset:37888
	ds_read_b128 v[212:215], v160 offset:38912
	ds_read_b128 v[216:219], v160 offset:39936
	global_load_lds_dwordx4 v[224:225], off
	v_lshl_add_u64 v[224:225], s[52:53], 0, v[132:133]
	s_mov_b32 m0, s19
	s_nop 0
	global_load_lds_dwordx4 v[224:225], off
	s_waitcnt vmcnt(8)
	s_waitcnt lgkmcnt(0)
	s_barrier
	s_setprio 1
	s_waitcnt lgkmcnt(0)
	v_mfma_f32_16x16x32_bf16 v[126:129], v[142:145], v[188:191], v[126:129]
	v_mfma_f32_16x16x32_bf16 v[122:125], v[150:153], v[188:191], v[122:125]
	v_mfma_f32_16x16x32_bf16 v[110:113], v[142:145], v[196:199], v[110:113]
	v_mfma_f32_16x16x32_bf16 v[106:109], v[150:153], v[196:199], v[106:109]
	v_mfma_f32_16x16x32_bf16 v[94:97], v[142:145], v[204:207], v[94:97]
	v_mfma_f32_16x16x32_bf16 v[90:93], v[150:153], v[204:207], v[90:93]
	v_mfma_f32_16x16x32_bf16 v[78:81], v[142:145], v[212:215], v[78:81]
	v_mfma_f32_16x16x32_bf16 v[74:77], v[150:153], v[212:215], v[74:77]
	v_mfma_f32_16x16x32_bf16 v[126:129], v[146:149], v[192:195], v[126:129]
	v_mfma_f32_16x16x32_bf16 v[122:125], v[154:157], v[192:195], v[122:125]
	v_mfma_f32_16x16x32_bf16 v[110:113], v[146:149], v[200:203], v[110:113]
	v_mfma_f32_16x16x32_bf16 v[106:109], v[154:157], v[200:203], v[106:109]
	v_mfma_f32_16x16x32_bf16 v[94:97], v[146:149], v[208:211], v[94:97]
	v_mfma_f32_16x16x32_bf16 v[90:93], v[154:157], v[208:211], v[90:93]
	v_mfma_f32_16x16x32_bf16 v[78:81], v[146:149], v[216:219], v[78:81]
	v_mfma_f32_16x16x32_bf16 v[74:77], v[154:157], v[216:219], v[74:77]
	v_mfma_f32_16x16x32_bf16 v[118:121], v[162:165], v[188:191], v[118:121]
	v_mfma_f32_16x16x32_bf16 v[114:117], v[170:173], v[188:191], v[114:117]
	v_mfma_f32_16x16x32_bf16 v[102:105], v[162:165], v[196:199], v[102:105]
	v_mfma_f32_16x16x32_bf16 v[98:101], v[170:173], v[196:199], v[98:101]
	v_mfma_f32_16x16x32_bf16 v[86:89], v[162:165], v[204:207], v[86:89]
	v_mfma_f32_16x16x32_bf16 v[82:85], v[170:173], v[204:207], v[82:85]
	v_mfma_f32_16x16x32_bf16 v[70:73], v[162:165], v[212:215], v[70:73]
	v_mfma_f32_16x16x32_bf16 v[66:69], v[170:173], v[212:215], v[66:69]
	v_mfma_f32_16x16x32_bf16 v[118:121], v[166:169], v[192:195], v[118:121]
	v_mfma_f32_16x16x32_bf16 v[114:117], v[184:187], v[192:195], v[114:117]
	v_mfma_f32_16x16x32_bf16 v[102:105], v[166:169], v[200:203], v[102:105]
	v_mfma_f32_16x16x32_bf16 v[98:101], v[184:187], v[200:203], v[98:101]
	v_mfma_f32_16x16x32_bf16 v[86:89], v[166:169], v[208:211], v[86:89]
	v_mfma_f32_16x16x32_bf16 v[82:85], v[184:187], v[208:211], v[82:85]
	v_mfma_f32_16x16x32_bf16 v[70:73], v[166:169], v[216:219], v[70:73]
	v_mfma_f32_16x16x32_bf16 v[66:69], v[184:187], v[216:219], v[66:69]
	s_setprio 0
	s_barrier
	s_add_i32 s52, s54, s2
	v_lshl_add_u64 v[174:175], v[174:175], 0, s[14:15]
	s_mov_b32 m0, s52
	ds_read_b128 v[188:191], v160 offset:49152
	ds_read_b128 v[192:195], v160 offset:50176
	ds_read_b128 v[196:199], v160 offset:51200
	ds_read_b128 v[200:203], v160 offset:52224
	ds_read_b128 v[204:207], v160 offset:53248
	ds_read_b128 v[208:211], v160 offset:54272
	ds_read_b128 v[212:215], v160 offset:55296
	ds_read_b128 v[216:219], v160 offset:56320
	global_load_lds_dwordx4 v[174:175], off
	s_add_i32 m0, s52, 0x2000
	s_add_u32 s4, s4, 0x40080
	v_lshl_add_u64 v[174:175], v[182:183], 0, s[14:15]
	s_addc_u32 s5, s5, 0
	s_add_i32 s52, s55, s2
	global_load_lds_dwordx4 v[174:175], off
	v_lshl_add_u64 v[174:175], s[4:5], 0, v[130:131]
	s_mov_b32 m0, s52
	s_nop 0
	global_load_lds_dwordx4 v[174:175], off
	v_lshl_add_u64 v[174:175], s[4:5], 0, v[132:133]
	s_add_i32 m0, s52, 0x2000
	s_nop 0
	global_load_lds_dwordx4 v[174:175], off
	v_lshl_add_u64 v[174:175], v[220:221], 0, s[14:15]
	s_mov_b32 m0, s21
	s_nop 0
	global_load_lds_dwordx4 v[174:175], off
	v_lshl_add_u64 v[174:175], v[222:223], 0, s[14:15]
	s_mov_b32 m0, s24
	s_nop 0
	global_load_lds_dwordx4 v[174:175], off
	s_waitcnt vmcnt(8)
	s_waitcnt lgkmcnt(0)
	s_barrier
	s_setprio 1
	s_waitcnt lgkmcnt(0)
	v_mfma_f32_16x16x32_bf16 v[60:63], v[142:145], v[188:191], v[60:63]
	v_mfma_f32_16x16x32_bf16 v[56:59], v[150:153], v[188:191], v[56:59]
	v_mfma_f32_16x16x32_bf16 v[44:47], v[142:145], v[196:199], v[44:47]
	v_mfma_f32_16x16x32_bf16 v[40:43], v[150:153], v[196:199], v[40:43]
	v_mfma_f32_16x16x32_bf16 v[28:31], v[142:145], v[204:207], v[28:31]
	v_mfma_f32_16x16x32_bf16 v[24:27], v[150:153], v[204:207], v[24:27]
	v_mfma_f32_16x16x32_bf16 v[12:15], v[142:145], v[212:215], v[12:15]
	v_mfma_f32_16x16x32_bf16 v[8:11], v[150:153], v[212:215], v[8:11]
	v_mfma_f32_16x16x32_bf16 v[60:63], v[146:149], v[192:195], v[60:63]
	v_mfma_f32_16x16x32_bf16 v[56:59], v[154:157], v[192:195], v[56:59]
	v_mfma_f32_16x16x32_bf16 v[44:47], v[146:149], v[200:203], v[44:47]
	v_mfma_f32_16x16x32_bf16 v[40:43], v[154:157], v[200:203], v[40:43]
	v_mfma_f32_16x16x32_bf16 v[28:31], v[146:149], v[208:211], v[28:31]
	v_mfma_f32_16x16x32_bf16 v[24:27], v[154:157], v[208:211], v[24:27]
	v_mfma_f32_16x16x32_bf16 v[12:15], v[146:149], v[216:219], v[12:15]
	v_mfma_f32_16x16x32_bf16 v[8:11], v[154:157], v[216:219], v[8:11]
	v_mfma_f32_16x16x32_bf16 v[52:55], v[162:165], v[188:191], v[52:55]
	v_mfma_f32_16x16x32_bf16 v[48:51], v[170:173], v[188:191], v[48:51]
	v_mfma_f32_16x16x32_bf16 v[36:39], v[162:165], v[196:199], v[36:39]
	v_mfma_f32_16x16x32_bf16 v[32:35], v[170:173], v[196:199], v[32:35]
	v_mfma_f32_16x16x32_bf16 v[20:23], v[162:165], v[204:207], v[20:23]
	v_mfma_f32_16x16x32_bf16 v[16:19], v[170:173], v[204:207], v[16:19]
	v_mfma_f32_16x16x32_bf16 v[4:7], v[162:165], v[212:215], v[4:7]
	v_mfma_f32_16x16x32_bf16 v[0:3], v[170:173], v[212:215], v[0:3]
	v_mfma_f32_16x16x32_bf16 v[52:55], v[166:169], v[192:195], v[52:55]
	v_mfma_f32_16x16x32_bf16 v[48:51], v[184:187], v[192:195], v[48:51]
	v_mfma_f32_16x16x32_bf16 v[36:39], v[166:169], v[200:203], v[36:39]
	v_mfma_f32_16x16x32_bf16 v[32:35], v[184:187], v[200:203], v[32:35]
	v_mfma_f32_16x16x32_bf16 v[20:23], v[166:169], v[208:211], v[20:23]
	v_mfma_f32_16x16x32_bf16 v[16:19], v[184:187], v[208:211], v[16:19]
	v_mfma_f32_16x16x32_bf16 v[4:7], v[166:169], v[216:219], v[4:7]
	v_mfma_f32_16x16x32_bf16 v[0:3], v[184:187], v[216:219], v[0:3]
	s_setprio 0
	s_barrier
	s_add_i32 s49, s49, 2
	s_add_u32 s42, s42, 0x100
	s_addc_u32 s43, s43, 0
	s_add_u32 s41, s41, 0x100
	s_addc_u32 s45, s45, 0
	s_cmp_gt_u32 s49, 13
	s_cbranch_scc0 .LBB0_929
	s_and_b64 vcc, exec, s[8:9]
	s_cbranch_vccz .LBB0_932
	s_barrier
